# GLA gate pairs interleaved (no s_nop padding, la formed by mul+fma instead of packed add/mul); softplus(-lambda) of the RG-LRU computed once per launch into a workspace table instead of per wave per c
# speedup vs baseline: 1.0177x; 1.0021x over previous
; __device__ __forceinline__ float bf2f(bf16_t b) { return __uint_as_float(((unsigned)b) << 16); }
; __device__ __forceinline__ bf16_t f2bf(float f) { unsigned u = __float_as_uint(f); return (bf16_t)((u + 0x7fffu + ((u >> 16) & 1u)) >> 16); }
; template <int MODE> __device__ void mixer_lru(const Params& p, int l, int n, LAS unsigned char* lds) {
;     ...
;         {
;             const int ch = tid;
;             const float cw0 = p.in[4][(size_t)(l * 4 + 0) * 512 + ch], cw1 = p.in[4][(size_t)(l * 4 + 1) * 512 + ch], cw2 = p.in[4][(size_t)(l * 4 + 2) * 512 + ch], cw3 = p.in[4][(size_t)(l * 4 + 3) * 512 + ch];
;             const float cb = p.in[5][(size_t)l * 512 + ch];
;             bf16_t xs[67];
; #pragma unroll
;             for (int i = 0; i < 67; ++i) { const int s_ = t0 - 2 + i; const int sc = s_ < 0 ? 0 : (s_ >= S ? S - 1 : s_); const bf16_t v = proj[(size_t)sc * DINP + ch]; xs[i] = s_ == sc ? v : (bf16_t)0; }
; #pragma unroll
;             for (int t = 0; t < 64; ++t) { const float xc = cb + cw0 * bf2f(xs[t]) + cw1 * bf2f(xs[t + 1]) + cw2 * bf2f(xs[t + 2]) + cw3 * bf2f(xs[t + 3]); XC[t * 520 + ch] = f2bf(xc); }
.LBB0_192:
	v_mov_b32_e32 v100, v245
	s_lshl_b32 s28, s4, 6
	v_readlane_b32 s0, v253, 16
	v_readlane_b32 s1, v253, 17
	v_readlane_b32 s88, v255, 22
	v_readlane_b32 s89, v255, 23
	v_readfirstlane_b32 s29, v100
	v_and_b32_e32 v0, 0xff, v100
	v_lshlrev_b32_e32 v1, 3, v0
	v_lshlrev_b32_e32 v0, 2, v0
	s_nop 4
	s_lshr_b32 s29, s29, 8
	global_load_dwordx2 v[2:3], v1, s[14:15]
	global_load_dwordx2 v[4:5], v1, s[88:89]
	global_load_dwordx2 v[6:7], v1, s[8:9]
	global_load_dwordx2 v[8:9], v1, s[10:11]
	global_load_dwordx2 v[10:11], v1, s[12:13]
	s_lshl_b32 s30, s29, 5
	s_add_i32 s30, s30, s28
	s_add_i32 s30, s30, -2
	s_max_i32 s31, s30, 0
	s_cmp_eq_u32 s31, s30
	s_cselect_b32 s92, -1, 0
	s_mul_i32 s31, s31, 0x1600
	s_add_u32 s90, s0, s31
	s_addc_u32 s91, s1, 0
	global_load_dword v12, v0, s[90:91]
	s_add_i32 s34, s30, 1
	s_max_i32 s31, s34, 0
	s_cmp_eq_u32 s31, s34
	s_cselect_b32 s93, -1, 0
	s_mul_i32 s31, s31, 0x1600
	s_add_u32 s90, s0, s31
	s_addc_u32 s91, s1, 0
	global_load_dword v13, v0, s[90:91]
	s_add_i32 s31, s30, 2
	s_mul_i32 s31, s31, 0x1600
	s_add_u32 s90, s0, s31
	s_addc_u32 s91, s1, 0
	global_load_dword v14, v0, s[90:91]
	s_add_u32 s90, s90, 0x1600
	s_addc_u32 s91, s91, 0
	global_load_dword v15, v0, s[90:91]
	s_add_u32 s90, s90, 0x1600
	s_addc_u32 s91, s91, 0
	global_load_dword v16, v0, s[90:91]
	s_add_u32 s90, s90, 0x1600
	s_addc_u32 s91, s91, 0
	global_load_dword v17, v0, s[90:91]
	s_add_u32 s90, s90, 0x1600
	s_addc_u32 s91, s91, 0
	global_load_dword v18, v0, s[90:91]
	s_add_u32 s90, s90, 0x1600
	s_addc_u32 s91, s91, 0
	global_load_dword v19, v0, s[90:91]
	s_add_u32 s90, s90, 0x1600
	s_addc_u32 s91, s91, 0
	global_load_dword v20, v0, s[90:91]
	s_add_u32 s90, s90, 0x1600
	s_addc_u32 s91, s91, 0
	global_load_dword v21, v0, s[90:91]
	s_add_u32 s90, s90, 0x1600
	s_addc_u32 s91, s91, 0
	global_load_dword v22, v0, s[90:91]
	s_add_u32 s90, s90, 0x1600
	s_addc_u32 s91, s91, 0
	global_load_dword v23, v0, s[90:91]
	s_add_u32 s90, s90, 0x1600
	s_addc_u32 s91, s91, 0
	global_load_dword v24, v0, s[90:91]
	s_add_u32 s90, s90, 0x1600
	s_addc_u32 s91, s91, 0
	global_load_dword v25, v0, s[90:91]
	s_add_u32 s90, s90, 0x1600
	s_addc_u32 s91, s91, 0
	global_load_dword v26, v0, s[90:91]
	s_add_u32 s90, s90, 0x1600
	s_addc_u32 s91, s91, 0
	global_load_dword v27, v0, s[90:91]
	s_add_u32 s90, s90, 0x1600
	s_addc_u32 s91, s91, 0
	global_load_dword v28, v0, s[90:91]
	s_add_u32 s90, s90, 0x1600
	s_addc_u32 s91, s91, 0
	global_load_dword v29, v0, s[90:91]
	s_add_u32 s90, s90, 0x1600
	s_addc_u32 s91, s91, 0
	global_load_dword v30, v0, s[90:91]
	s_add_u32 s90, s90, 0x1600
	s_addc_u32 s91, s91, 0
	global_load_dword v31, v0, s[90:91]
	s_add_u32 s90, s90, 0x1600
	s_addc_u32 s91, s91, 0
	global_load_dword v32, v0, s[90:91]
	s_add_u32 s90, s90, 0x1600
	s_addc_u32 s91, s91, 0
	global_load_dword v33, v0, s[90:91]
	s_add_u32 s90, s90, 0x1600
	s_addc_u32 s91, s91, 0
	global_load_dword v34, v0, s[90:91]
	s_add_u32 s90, s90, 0x1600
	s_addc_u32 s91, s91, 0
	global_load_dword v35, v0, s[90:91]
	s_add_u32 s90, s90, 0x1600
	s_addc_u32 s91, s91, 0
	global_load_dword v36, v0, s[90:91]
	s_add_u32 s90, s90, 0x1600
	s_addc_u32 s91, s91, 0
	global_load_dword v37, v0, s[90:91]
	s_add_u32 s90, s90, 0x1600
	s_addc_u32 s91, s91, 0
	global_load_dword v38, v0, s[90:91]
	s_add_u32 s90, s90, 0x1600
	s_addc_u32 s91, s91, 0
	global_load_dword v39, v0, s[90:91]
	s_add_u32 s90, s90, 0x1600
	s_addc_u32 s91, s91, 0
	global_load_dword v40, v0, s[90:91]
	s_add_u32 s90, s90, 0x1600
	s_addc_u32 s91, s91, 0
	global_load_dword v41, v0, s[90:91]
	s_add_u32 s90, s90, 0x1600
	s_addc_u32 s91, s91, 0
	global_load_dword v42, v0, s[90:91]
	s_add_u32 s90, s90, 0x1600
	s_addc_u32 s91, s91, 0
	global_load_dword v43, v0, s[90:91]
	s_add_u32 s90, s90, 0x1600
	s_addc_u32 s91, s91, 0
	global_load_dword v44, v0, s[90:91]
	s_add_u32 s90, s90, 0x1600
	s_addc_u32 s91, s91, 0
	global_load_dword v45, v0, s[90:91]
	s_add_i32 s34, s30, 34
	s_min_i32 s31, s34, 0x3fff
	s_cmp_eq_u32 s31, s34
	s_cselect_b32 s94, -1, 0
	s_mul_i32 s31, s31, 0x1600
	s_add_u32 s90, s0, s31
	s_addc_u32 s91, s1, 0
	global_load_dword v46, v0, s[90:91]
	s_mul_i32 s95, s29, 0x8200
	v_add_u32_e32 v92, s95, v0
	s_waitcnt vmcnt(31)
	v_and_b32_e32 v12, s92, v12
	v_lshlrev_b32_e32 v48, 16, v12
	v_and_b32_e32 v12, 0xffff0000, v12
	v_and_b32_e32 v13, s93, v13
	v_lshlrev_b32_e32 v49, 16, v13
	v_and_b32_e32 v13, 0xffff0000, v13
	v_lshlrev_b32_e32 v50, 16, v14
	v_and_b32_e32 v14, 0xffff0000, v14
	v_lshlrev_b32_e32 v51, 16, v15
	v_and_b32_e32 v15, 0xffff0000, v15
	v_fma_f32 v84, v4, v48, v2
	v_fma_f32 v85, v5, v12, v3
	v_fmac_f32_e32 v84, v6, v49
	v_fmac_f32_e32 v85, v7, v13
	v_fmac_f32_e32 v84, v8, v50
	v_fmac_f32_e32 v85, v9, v14
	v_fmac_f32_e32 v84, v10, v51
	v_fmac_f32_e32 v85, v11, v15
	v_cvt_pk_bf16_f32 v84, v84, v85
	ds_write_b32 v92, v84
	s_waitcnt vmcnt(30)
	v_lshlrev_b32_e32 v52, 16, v16
	v_and_b32_e32 v16, 0xffff0000, v16
	v_fma_f32 v86, v4, v49, v2
	v_fma_f32 v87, v5, v13, v3
	v_fmac_f32_e32 v86, v6, v50
	v_fmac_f32_e32 v87, v7, v14
	v_fmac_f32_e32 v86, v8, v51
	v_fmac_f32_e32 v87, v9, v15
	v_fmac_f32_e32 v86, v10, v52
	v_fmac_f32_e32 v87, v11, v16
	v_cvt_pk_bf16_f32 v86, v86, v87
	ds_write_b32 v92, v86 offset:1040
	s_waitcnt vmcnt(29)
	v_lshlrev_b32_e32 v53, 16, v17
	v_and_b32_e32 v17, 0xffff0000, v17
	v_fma_f32 v84, v4, v50, v2
	v_fma_f32 v85, v5, v14, v3
	v_fmac_f32_e32 v84, v6, v51
	v_fmac_f32_e32 v85, v7, v15
	v_fmac_f32_e32 v84, v8, v52
	v_fmac_f32_e32 v85, v9, v16
	v_fmac_f32_e32 v84, v10, v53
	v_fmac_f32_e32 v85, v11, v17
	v_cvt_pk_bf16_f32 v84, v84, v85
	ds_write_b32 v92, v84 offset:2080
	s_waitcnt vmcnt(28)
; __device__ __forceinline__ float bf2f(bf16_t b) { return __uint_as_float(((unsigned)b) << 16); }
; __device__ __forceinline__ bf16_t f2bf(float f) { unsigned u = __float_as_uint(f); return (bf16_t)((u + 0x7fffu + ((u >> 16) & 1u)) >> 16); }
; template <int MODE> __device__ void mixer_lru(const Params& p, int l, int n, LAS unsigned char* lds) {
;     ...
;             for (int i = 0; i < 67; ++i) { const int s_ = t0 - 2 + i; const int sc = s_ < 0 ? 0 : (s_ >= S ? S - 1 : s_); const bf16_t v = proj[(size_t)sc * DINP + ch]; xs[i] = s_ == sc ? v : (bf16_t)0; }
; #pragma unroll
;             for (int t = 0; t < 64; ++t) { const float xc = cb + cw0 * bf2f(xs[t]) + cw1 * bf2f(xs[t + 1]) + cw2 * bf2f(xs[t + 2]) + cw3 * bf2f(xs[t + 3]); XC[t * 520 + ch] = f2bf(xc); }
	v_lshlrev_b32_e32 v54, 16, v18
	v_and_b32_e32 v18, 0xffff0000, v18
	v_fma_f32 v86, v4, v51, v2
	v_fma_f32 v87, v5, v15, v3
	v_fmac_f32_e32 v86, v6, v52
	v_fmac_f32_e32 v87, v7, v16
	v_fmac_f32_e32 v86, v8, v53
	v_fmac_f32_e32 v87, v9, v17
	v_fmac_f32_e32 v86, v10, v54
	v_fmac_f32_e32 v87, v11, v18
	v_cvt_pk_bf16_f32 v86, v86, v87
	ds_write_b32 v92, v86 offset:3120
	s_waitcnt vmcnt(27)
	v_lshlrev_b32_e32 v55, 16, v19
	v_and_b32_e32 v19, 0xffff0000, v19
	v_fma_f32 v84, v4, v52, v2
	v_fma_f32 v85, v5, v16, v3
	v_fmac_f32_e32 v84, v6, v53
	v_fmac_f32_e32 v85, v7, v17
	v_fmac_f32_e32 v84, v8, v54
	v_fmac_f32_e32 v85, v9, v18
	v_fmac_f32_e32 v84, v10, v55
	v_fmac_f32_e32 v85, v11, v19
	v_cvt_pk_bf16_f32 v84, v84, v85
	ds_write_b32 v92, v84 offset:4160
	s_waitcnt vmcnt(26)
	v_lshlrev_b32_e32 v56, 16, v20
	v_and_b32_e32 v20, 0xffff0000, v20
	v_fma_f32 v86, v4, v53, v2
	v_fma_f32 v87, v5, v17, v3
	v_fmac_f32_e32 v86, v6, v54
	v_fmac_f32_e32 v87, v7, v18
	v_fmac_f32_e32 v86, v8, v55
	v_fmac_f32_e32 v87, v9, v19
	v_fmac_f32_e32 v86, v10, v56
	v_fmac_f32_e32 v87, v11, v20
	v_cvt_pk_bf16_f32 v86, v86, v87
	ds_write_b32 v92, v86 offset:5200
	s_waitcnt vmcnt(25)
	v_lshlrev_b32_e32 v57, 16, v21
	v_and_b32_e32 v21, 0xffff0000, v21
	v_fma_f32 v84, v4, v54, v2
	v_fma_f32 v85, v5, v18, v3
	v_fmac_f32_e32 v84, v6, v55
	v_fmac_f32_e32 v85, v7, v19
	v_fmac_f32_e32 v84, v8, v56
	v_fmac_f32_e32 v85, v9, v20
	v_fmac_f32_e32 v84, v10, v57
	v_fmac_f32_e32 v85, v11, v21
	v_cvt_pk_bf16_f32 v84, v84, v85
	ds_write_b32 v92, v84 offset:6240
	s_waitcnt vmcnt(24)
	v_lshlrev_b32_e32 v58, 16, v22
	v_and_b32_e32 v22, 0xffff0000, v22
	v_fma_f32 v86, v4, v55, v2
	v_fma_f32 v87, v5, v19, v3
	v_fmac_f32_e32 v86, v6, v56
	v_fmac_f32_e32 v87, v7, v20
	v_fmac_f32_e32 v86, v8, v57
	v_fmac_f32_e32 v87, v9, v21
	v_fmac_f32_e32 v86, v10, v58
	v_fmac_f32_e32 v87, v11, v22
	v_cvt_pk_bf16_f32 v86, v86, v87
	ds_write_b32 v92, v86 offset:7280
	s_waitcnt vmcnt(23)
	v_lshlrev_b32_e32 v59, 16, v23
	v_and_b32_e32 v23, 0xffff0000, v23
	v_fma_f32 v84, v4, v56, v2
	v_fma_f32 v85, v5, v20, v3
	v_fmac_f32_e32 v84, v6, v57
	v_fmac_f32_e32 v85, v7, v21
	v_fmac_f32_e32 v84, v8, v58
	v_fmac_f32_e32 v85, v9, v22
	v_fmac_f32_e32 v84, v10, v59
	v_fmac_f32_e32 v85, v11, v23
	v_cvt_pk_bf16_f32 v84, v84, v85
	ds_write_b32 v92, v84 offset:8320
	s_waitcnt vmcnt(22)
	v_lshlrev_b32_e32 v60, 16, v24
	v_and_b32_e32 v24, 0xffff0000, v24
	v_fma_f32 v86, v4, v57, v2
	v_fma_f32 v87, v5, v21, v3
	v_fmac_f32_e32 v86, v6, v58
	v_fmac_f32_e32 v87, v7, v22
	v_fmac_f32_e32 v86, v8, v59
	v_fmac_f32_e32 v87, v9, v23
	v_fmac_f32_e32 v86, v10, v60
	v_fmac_f32_e32 v87, v11, v24
	v_cvt_pk_bf16_f32 v86, v86, v87
	ds_write_b32 v92, v86 offset:9360
	s_waitcnt vmcnt(21)
	v_lshlrev_b32_e32 v61, 16, v25
	v_and_b32_e32 v25, 0xffff0000, v25
	v_fma_f32 v84, v4, v58, v2
	v_fma_f32 v85, v5, v22, v3
	v_fmac_f32_e32 v84, v6, v59
	v_fmac_f32_e32 v85, v7, v23
	v_fmac_f32_e32 v84, v8, v60
	v_fmac_f32_e32 v85, v9, v24
	v_fmac_f32_e32 v84, v10, v61
	v_fmac_f32_e32 v85, v11, v25
	v_cvt_pk_bf16_f32 v84, v84, v85
	ds_write_b32 v92, v84 offset:10400
	s_waitcnt vmcnt(20)
	v_lshlrev_b32_e32 v62, 16, v26
	v_and_b32_e32 v26, 0xffff0000, v26
	v_fma_f32 v86, v4, v59, v2
	v_fma_f32 v87, v5, v23, v3
	v_fmac_f32_e32 v86, v6, v60
	v_fmac_f32_e32 v87, v7, v24
	v_fmac_f32_e32 v86, v8, v61
	v_fmac_f32_e32 v87, v9, v25
	v_fmac_f32_e32 v86, v10, v62
	v_fmac_f32_e32 v87, v11, v26
	v_cvt_pk_bf16_f32 v86, v86, v87
	ds_write_b32 v92, v86 offset:11440
	s_waitcnt vmcnt(19)
	v_lshlrev_b32_e32 v63, 16, v27
	v_and_b32_e32 v27, 0xffff0000, v27
	v_fma_f32 v84, v4, v60, v2
	v_fma_f32 v85, v5, v24, v3
	v_fmac_f32_e32 v84, v6, v61
	v_fmac_f32_e32 v85, v7, v25
	v_fmac_f32_e32 v84, v8, v62
	v_fmac_f32_e32 v85, v9, v26
	v_fmac_f32_e32 v84, v10, v63
	v_fmac_f32_e32 v85, v11, v27
	v_cvt_pk_bf16_f32 v84, v84, v85
	ds_write_b32 v92, v84 offset:12480
	s_waitcnt vmcnt(18)
	v_lshlrev_b32_e32 v64, 16, v28
	v_and_b32_e32 v28, 0xffff0000, v28
	v_fma_f32 v86, v4, v61, v2
	v_fma_f32 v87, v5, v25, v3
	v_fmac_f32_e32 v86, v6, v62
	v_fmac_f32_e32 v87, v7, v26
	v_fmac_f32_e32 v86, v8, v63
	v_fmac_f32_e32 v87, v9, v27
	v_fmac_f32_e32 v86, v10, v64
	v_fmac_f32_e32 v87, v11, v28
	v_cvt_pk_bf16_f32 v86, v86, v87
	ds_write_b32 v92, v86 offset:13520
	s_waitcnt vmcnt(17)
	v_lshlrev_b32_e32 v65, 16, v29
	v_and_b32_e32 v29, 0xffff0000, v29
	v_fma_f32 v84, v4, v62, v2
	v_fma_f32 v85, v5, v26, v3
	v_fmac_f32_e32 v84, v6, v63
	v_fmac_f32_e32 v85, v7, v27
	v_fmac_f32_e32 v84, v8, v64
	v_fmac_f32_e32 v85, v9, v28
	v_fmac_f32_e32 v84, v10, v65
	v_fmac_f32_e32 v85, v11, v29
	v_cvt_pk_bf16_f32 v84, v84, v85
	ds_write_b32 v92, v84 offset:14560
	s_waitcnt vmcnt(16)
	v_lshlrev_b32_e32 v66, 16, v30
	v_and_b32_e32 v30, 0xffff0000, v30
	v_fma_f32 v86, v4, v63, v2
	v_fma_f32 v87, v5, v27, v3
	v_fmac_f32_e32 v86, v6, v64
	v_fmac_f32_e32 v87, v7, v28
	v_fmac_f32_e32 v86, v8, v65
	v_fmac_f32_e32 v87, v9, v29
	v_fmac_f32_e32 v86, v10, v66
	v_fmac_f32_e32 v87, v11, v30
	v_cvt_pk_bf16_f32 v86, v86, v87
	ds_write_b32 v92, v86 offset:15600
	s_waitcnt vmcnt(15)
	v_lshlrev_b32_e32 v67, 16, v31
	v_and_b32_e32 v31, 0xffff0000, v31
	v_fma_f32 v84, v4, v64, v2
	v_fma_f32 v85, v5, v28, v3
	v_fmac_f32_e32 v84, v6, v65
	v_fmac_f32_e32 v85, v7, v29
	v_fmac_f32_e32 v84, v8, v66
	v_fmac_f32_e32 v85, v9, v30
	v_fmac_f32_e32 v84, v10, v67
	v_fmac_f32_e32 v85, v11, v31
	v_cvt_pk_bf16_f32 v84, v84, v85
	ds_write_b32 v92, v84 offset:16640
	s_waitcnt vmcnt(14)
; __device__ __forceinline__ float bf2f(bf16_t b) { return __uint_as_float(((unsigned)b) << 16); }
; __device__ __forceinline__ bf16_t f2bf(float f) { unsigned u = __float_as_uint(f); return (bf16_t)((u + 0x7fffu + ((u >> 16) & 1u)) >> 16); }
; template <int DIR> __device__ __forceinline__ void lru_dir(const Params& p, int l, int n, int h, int lane, LAS bf16_t* XC, LAS float* STA, LAS float* STU) {
;     const int c = lane & 15, q = lane >> 4, j = lane, t0 = n * 64;
;     unsigned char* ws = p.ws;
;     bf16_t* y = (bf16_t*)(ws + WS_H); bf16_t* PB = (bf16_t*)(ws + WS_PB);
;     const bf16_t* LW = (const bf16_t*)(ws + WS_LRUW);
;     float* Aprod = (float*)(ws + WS_AP); float* Hend = (float*)(ws + WS_HE);
;     const float* lam = p.in[10] + (size_t)(l * 2 + DIR) * 512 + 64 * h; const float* b_a = p.in[7] + (size_t)(l * 2 + DIR) * 512 + 64 * h; const float* b_x = p.in[9] + (size_t)(l * 2 + DIR) * 512 + 64 * h;
;     const bf16_t* LWa = LW + ((size_t)(DIR * 2 + 0) * 8 + h) * 4096 + c * 64 + 8 * q; const bf16_t* LWx = LW + ((size_t)(DIR * 2 + 1) * 8 + h) * 4096 + c * 64 + 8 * q;
;     bf16x8 wa[4][2], wx[4][2]; f32x4 sp4[4], ba4[4], bx4[4];
; #pragma unroll
;     for (int nf = 0; nf < 4; ++nf) {
; #pragma unroll
;         for (int ks = 0; ks < 2; ++ks) { wa[nf][ks] = *(const bf16x8*)(LWa + nf * 1024 + 32 * ks); wx[nf][ks] = *(const bf16x8*)(LWx + nf * 1024 + 32 * ks); }
;         const f32x4 lam4 = *(const f32x4*)(lam + 16 * nf + 4 * q); ba4[nf] = *(const f32x4*)(b_a + 16 * nf + 4 * q); bx4[nf] = *(const f32x4*)(b_x + 16 * nf + 4 * q);
; template <int MODE> __device__ void mixer_lru(const Params& p, int l, int n, LAS unsigned char* lds) {
;     ...
;             for (int i = 0; i < 67; ++i) { const int s_ = t0 - 2 + i; const int sc = s_ < 0 ? 0 : (s_ >= S ? S - 1 : s_); const bf16_t v = proj[(size_t)sc * DINP + ch]; xs[i] = s_ == sc ? v : (bf16_t)0; }
; #pragma unroll
;             for (int t = 0; t < 64; ++t) { const float xc = cb + cw0 * bf2f(xs[t]) + cw1 * bf2f(xs[t + 1]) + cw2 * bf2f(xs[t + 2]) + cw3 * bf2f(xs[t + 3]); XC[t * 520 + ch] = f2bf(xc); }
;         }
;         __syncthreads();
	v_lshlrev_b32_e32 v68, 16, v32
	v_and_b32_e32 v32, 0xffff0000, v32
	v_fma_f32 v86, v4, v65, v2
	v_fma_f32 v87, v5, v29, v3
	v_fmac_f32_e32 v86, v6, v66
	v_fmac_f32_e32 v87, v7, v30
	v_fmac_f32_e32 v86, v8, v67
	v_fmac_f32_e32 v87, v9, v31
	v_fmac_f32_e32 v86, v10, v68
	v_fmac_f32_e32 v87, v11, v32
	v_cvt_pk_bf16_f32 v86, v86, v87
	ds_write_b32 v92, v86 offset:17680
	s_waitcnt vmcnt(13)
	v_lshlrev_b32_e32 v69, 16, v33
	v_and_b32_e32 v33, 0xffff0000, v33
	v_fma_f32 v84, v4, v66, v2
	v_fma_f32 v85, v5, v30, v3
	v_fmac_f32_e32 v84, v6, v67
	v_fmac_f32_e32 v85, v7, v31
	v_fmac_f32_e32 v84, v8, v68
	v_fmac_f32_e32 v85, v9, v32
	v_fmac_f32_e32 v84, v10, v69
	v_fmac_f32_e32 v85, v11, v33
	v_cvt_pk_bf16_f32 v84, v84, v85
	ds_write_b32 v92, v84 offset:18720
	s_waitcnt vmcnt(12)
	v_lshlrev_b32_e32 v70, 16, v34
	v_and_b32_e32 v34, 0xffff0000, v34
	v_fma_f32 v86, v4, v67, v2
	v_fma_f32 v87, v5, v31, v3
	v_fmac_f32_e32 v86, v6, v68
	v_fmac_f32_e32 v87, v7, v32
	v_fmac_f32_e32 v86, v8, v69
	v_fmac_f32_e32 v87, v9, v33
	v_fmac_f32_e32 v86, v10, v70
	v_fmac_f32_e32 v87, v11, v34
	v_cvt_pk_bf16_f32 v86, v86, v87
	ds_write_b32 v92, v86 offset:19760
	s_waitcnt vmcnt(11)
	v_lshlrev_b32_e32 v71, 16, v35
	v_and_b32_e32 v35, 0xffff0000, v35
	v_fma_f32 v84, v4, v68, v2
	v_fma_f32 v85, v5, v32, v3
	v_fmac_f32_e32 v84, v6, v69
	v_fmac_f32_e32 v85, v7, v33
	v_fmac_f32_e32 v84, v8, v70
	v_fmac_f32_e32 v85, v9, v34
	v_fmac_f32_e32 v84, v10, v71
	v_fmac_f32_e32 v85, v11, v35
	v_cvt_pk_bf16_f32 v84, v84, v85
	ds_write_b32 v92, v84 offset:20800
	s_waitcnt vmcnt(10)
	v_lshlrev_b32_e32 v72, 16, v36
	v_and_b32_e32 v36, 0xffff0000, v36
	v_fma_f32 v86, v4, v69, v2
	v_fma_f32 v87, v5, v33, v3
	v_fmac_f32_e32 v86, v6, v70
	v_fmac_f32_e32 v87, v7, v34
	v_fmac_f32_e32 v86, v8, v71
	v_fmac_f32_e32 v87, v9, v35
	v_fmac_f32_e32 v86, v10, v72
	v_fmac_f32_e32 v87, v11, v36
	v_cvt_pk_bf16_f32 v86, v86, v87
	ds_write_b32 v92, v86 offset:21840
	s_waitcnt vmcnt(9)
	v_lshlrev_b32_e32 v73, 16, v37
	v_and_b32_e32 v37, 0xffff0000, v37
	v_fma_f32 v84, v4, v70, v2
	v_fma_f32 v85, v5, v34, v3
	v_fmac_f32_e32 v84, v6, v71
	v_fmac_f32_e32 v85, v7, v35
	v_fmac_f32_e32 v84, v8, v72
	v_fmac_f32_e32 v85, v9, v36
	v_fmac_f32_e32 v84, v10, v73
	v_fmac_f32_e32 v85, v11, v37
	v_cvt_pk_bf16_f32 v84, v84, v85
	ds_write_b32 v92, v84 offset:22880
	s_waitcnt vmcnt(8)
	v_lshlrev_b32_e32 v74, 16, v38
	v_and_b32_e32 v38, 0xffff0000, v38
	v_fma_f32 v86, v4, v71, v2
	v_fma_f32 v87, v5, v35, v3
	v_fmac_f32_e32 v86, v6, v72
	v_fmac_f32_e32 v87, v7, v36
	v_fmac_f32_e32 v86, v8, v73
	v_fmac_f32_e32 v87, v9, v37
	v_fmac_f32_e32 v86, v10, v74
	v_fmac_f32_e32 v87, v11, v38
	v_cvt_pk_bf16_f32 v86, v86, v87
	ds_write_b32 v92, v86 offset:23920
	s_waitcnt vmcnt(7)
	v_lshlrev_b32_e32 v75, 16, v39
	v_and_b32_e32 v39, 0xffff0000, v39
	v_fma_f32 v84, v4, v72, v2
	v_fma_f32 v85, v5, v36, v3
	v_fmac_f32_e32 v84, v6, v73
	v_fmac_f32_e32 v85, v7, v37
	v_fmac_f32_e32 v84, v8, v74
	v_fmac_f32_e32 v85, v9, v38
	v_fmac_f32_e32 v84, v10, v75
	v_fmac_f32_e32 v85, v11, v39
	v_cvt_pk_bf16_f32 v84, v84, v85
	ds_write_b32 v92, v84 offset:24960
	s_waitcnt vmcnt(6)
	v_lshlrev_b32_e32 v76, 16, v40
	v_and_b32_e32 v40, 0xffff0000, v40
	v_fma_f32 v86, v4, v73, v2
	v_fma_f32 v87, v5, v37, v3
	v_fmac_f32_e32 v86, v6, v74
	v_fmac_f32_e32 v87, v7, v38
	v_fmac_f32_e32 v86, v8, v75
	v_fmac_f32_e32 v87, v9, v39
	v_fmac_f32_e32 v86, v10, v76
	v_fmac_f32_e32 v87, v11, v40
	v_cvt_pk_bf16_f32 v86, v86, v87
	ds_write_b32 v92, v86 offset:26000
	s_waitcnt vmcnt(5)
	v_lshlrev_b32_e32 v77, 16, v41
	v_and_b32_e32 v41, 0xffff0000, v41
	v_fma_f32 v84, v4, v74, v2
	v_fma_f32 v85, v5, v38, v3
	v_fmac_f32_e32 v84, v6, v75
	v_fmac_f32_e32 v85, v7, v39
	v_fmac_f32_e32 v84, v8, v76
	v_fmac_f32_e32 v85, v9, v40
	v_fmac_f32_e32 v84, v10, v77
	v_fmac_f32_e32 v85, v11, v41
	v_cvt_pk_bf16_f32 v84, v84, v85
	ds_write_b32 v92, v84 offset:27040
	s_waitcnt vmcnt(4)
	v_lshlrev_b32_e32 v78, 16, v42
	v_and_b32_e32 v42, 0xffff0000, v42
	v_fma_f32 v86, v4, v75, v2
	v_fma_f32 v87, v5, v39, v3
	v_fmac_f32_e32 v86, v6, v76
	v_fmac_f32_e32 v87, v7, v40
	v_fmac_f32_e32 v86, v8, v77
	v_fmac_f32_e32 v87, v9, v41
	v_fmac_f32_e32 v86, v10, v78
	v_fmac_f32_e32 v87, v11, v42
	v_cvt_pk_bf16_f32 v86, v86, v87
	ds_write_b32 v92, v86 offset:28080
	s_waitcnt vmcnt(3)
	v_lshlrev_b32_e32 v79, 16, v43
	v_and_b32_e32 v43, 0xffff0000, v43
	v_fma_f32 v84, v4, v76, v2
	v_fma_f32 v85, v5, v40, v3
	v_fmac_f32_e32 v84, v6, v77
	v_fmac_f32_e32 v85, v7, v41
	v_fmac_f32_e32 v84, v8, v78
	v_fmac_f32_e32 v85, v9, v42
	v_fmac_f32_e32 v84, v10, v79
	v_fmac_f32_e32 v85, v11, v43
	v_cvt_pk_bf16_f32 v84, v84, v85
	ds_write_b32 v92, v84 offset:29120
	s_waitcnt vmcnt(2)
	v_lshlrev_b32_e32 v80, 16, v44
	v_and_b32_e32 v44, 0xffff0000, v44
	v_fma_f32 v86, v4, v77, v2
	v_fma_f32 v87, v5, v41, v3
	v_fmac_f32_e32 v86, v6, v78
	v_fmac_f32_e32 v87, v7, v42
	v_fmac_f32_e32 v86, v8, v79
	v_fmac_f32_e32 v87, v9, v43
	v_fmac_f32_e32 v86, v10, v80
	v_fmac_f32_e32 v87, v11, v44
	v_cvt_pk_bf16_f32 v86, v86, v87
	ds_write_b32 v92, v86 offset:30160
	s_waitcnt vmcnt(1)
	v_lshlrev_b32_e32 v81, 16, v45
	v_and_b32_e32 v45, 0xffff0000, v45
	v_fma_f32 v84, v4, v78, v2
	v_fma_f32 v85, v5, v42, v3
	v_fmac_f32_e32 v84, v6, v79
	v_fmac_f32_e32 v85, v7, v43
	v_fmac_f32_e32 v84, v8, v80
	v_fmac_f32_e32 v85, v9, v44
	v_fmac_f32_e32 v84, v10, v81
	v_fmac_f32_e32 v85, v11, v45
	v_cvt_pk_bf16_f32 v84, v84, v85
	ds_write_b32 v92, v84 offset:31200
	s_waitcnt vmcnt(0)
	v_and_b32_e32 v46, s94, v46
	v_lshlrev_b32_e32 v82, 16, v46
	v_and_b32_e32 v46, 0xffff0000, v46
	v_fma_f32 v86, v4, v79, v2
	v_fma_f32 v87, v5, v43, v3
	v_fmac_f32_e32 v86, v6, v80
	v_fmac_f32_e32 v87, v7, v44
	v_fmac_f32_e32 v86, v8, v81
	v_fmac_f32_e32 v87, v9, v45
	v_fmac_f32_e32 v86, v10, v82
	v_fmac_f32_e32 v87, v11, v46
	v_cvt_pk_bf16_f32 v86, v86, v87
	ds_write_b32 v92, v86 offset:32240
	v_ashrrev_i32_e32 v102, 6, v100
	v_ashrrev_i32_e32 v103, 31, v102
	v_and_b32_e32 v127, 15, v100
	v_and_b32_e32 v124, 0xffffffc0, v100
	v_ashrrev_i32_e32 v125, 31, v124
	v_lshlrev_b32_e32 v176, 7, v127
	v_readlane_b32 s0, v254, 17
	v_lshlrev_b64 v[6:7], 13, v[102:103]
	v_readlane_b32 s1, v254, 18
	s_nop 1
	v_lshlrev_b64 v[112:113], 2, v[124:125]
	v_lshl_add_u64 v[114:115], s[0:1], 0, v[6:7]
	v_lshl_add_u64 v[6:7], v[114:115], 0, v[176:177]
	v_and_b32_e32 v176, 48, v100
	v_lshl_add_u64 v[0:1], s[16:17], 0, v[112:113]
	v_lshl_add_u64 v[80:81], v[6:7], 0, v[176:177]
	v_lshl_add_u64 v[76:77], v[0:1], 0, v[176:177]
	v_add_co_u32_e32 v0, vcc, 0x10000, v80
	v_lshl_add_u64 v[2:3], s[18:19], 0, v[112:113]
	v_lshl_add_u64 v[4:5], s[20:21], 0, v[112:113]
	s_mov_b64 s[0:1], 0x10000
	v_addc_co_u32_e32 v1, vcc, 0, v81, vcc
	s_waitcnt lgkmcnt(0)
	s_barrier
; template <int DIR> __device__ __forceinline__ void lru_dir(const Params& p, int l, int n, int h, int lane, LAS bf16_t* XC, LAS float* STA, LAS float* STU) {
;     ...
;     const float* lam = p.in[10] + (size_t)(l * 2 + DIR) * 512 + 64 * h; const float* b_a = p.in[7] + (size_t)(l * 2 + DIR) * 512 + 64 * h; const float* b_x = p.in[9] + (size_t)(l * 2 + DIR) * 512 + 64 * h;
;     const bf16_t* LWa = LW + ((size_t)(DIR * 2 + 0) * 8 + h) * 4096 + c * 64 + 8 * q; const bf16_t* LWx = LW + ((size_t)(DIR * 2 + 1) * 8 + h) * 4096 + c * 64 + 8 * q;
;     bf16x8 wa[4][2], wx[4][2]; f32x4 sp4[4], ba4[4], bx4[4];
; #pragma unroll
;     for (int nf = 0; nf < 4; ++nf) {
; #pragma unroll
;         for (int ks = 0; ks < 2; ++ks) { wa[nf][ks] = *(const bf16x8*)(LWa + nf * 1024 + 32 * ks); wx[nf][ks] = *(const bf16x8*)(LWx + nf * 1024 + 32 * ks); }
;         const f32x4 lam4 = *(const f32x4*)(lam + 16 * nf + 4 * q); ba4[nf] = *(const f32x4*)(b_a + 16 * nf + 4 * q); bx4[nf] = *(const f32x4*)(b_x + 16 * nf + 4 * q);
; #pragma unroll
;         for (int r = 0; r < 4; ++r) { const float e = __expf(-lam4[r]); const float l1p = e < 0.05f ? e * (1.0f - e * (0.5f - e * (0.33333334f - e * 0.25f))) : __logf(1.0f + e); sp4[nf][r] = -8.0f * l1p; }
;     }
	v_lshl_add_u64 v[78:79], v[80:81], 0, s[0:1]
	v_lshl_add_u64 v[88:89], v[2:3], 0, v[176:177]
	v_lshl_add_u64 v[92:93], v[4:5], 0, v[176:177]
	v_readlane_b32 s0, v255, 0
	v_readlane_b32 s1, v255, 1
	v_readlane_b32 s30, v254, 47
	v_readlane_b32 s31, v254, 48
	s_add_u32 s0, s0, 0x4000
	s_addc_u32 s1, s1, 0
	s_sub_u32 s0, s0, s30
	s_subb_u32 s1, s1, s31
	v_lshl_add_u64 v[76:77], v[76:77], 0, s[0:1]
	global_load_dwordx4 v[192:195], v[76:77], off
	global_load_dwordx4 v[196:199], v[76:77], off offset:64
	global_load_dwordx4 v[200:203], v[76:77], off offset:128
	global_load_dwordx4 v[204:207], v[76:77], off offset:192
	s_nop 0
	global_load_dwordx4 v[0:3], v[0:1], off
	s_nop 0
	global_load_dwordx4 v[4:7], v[80:81], off
	global_load_dwordx4 v[8:11], v[80:81], off offset:64
	global_load_dwordx4 v[12:15], v[78:79], off offset:64
	global_load_dwordx4 v[16:19], v[88:89], off
	global_load_dwordx4 v[20:23], v[92:93], off
	s_mov_b32 s6, 0x3d4ccccd
	s_waitcnt vmcnt(6)
	v_mov_b32_e32 v101, v192
	v_readlane_b32 s52, v254, 60
	v_readlane_b32 s56, v255, 0
	v_readlane_b32 s57, v255, 1
	s_mov_b32 s2, 0x1858000
	s_movk_i32 s7, 0x410
	v_readlane_b32 s53, v254, 61
	v_readlane_b32 s54, v254, 62
	v_readlane_b32 s55, v254, 63
	v_readlane_b32 s58, v255, 2
	v_readlane_b32 s59, v255, 3
	v_mov_b32_e32 v103, v193
	v_mov_b32_e32 v104, v194
	v_mov_b32_e32 v105, v195
	global_load_dwordx4 v[24:27], v[80:81], off offset:2048
	global_load_dwordx4 v[28:31], v[80:81], off offset:2112
	global_load_dwordx4 v[32:35], v[78:79], off offset:2048
	global_load_dwordx4 v[36:39], v[78:79], off offset:2112
	global_load_dwordx4 v[40:43], v[88:89], off offset:64
	global_load_dwordx4 v[44:47], v[92:93], off offset:64
	v_mov_b32_e32 v106, v196
	v_mov_b32_e32 v107, v197
	v_mov_b32_e32 v108, v198
	v_mov_b32_e32 v109, v199
	v_add_co_u32_e32 v52, vcc, 0x1000, v80
	s_nop 1
	v_addc_co_u32_e32 v53, vcc, 0, v81, vcc
	v_add_co_u32_e32 v60, vcc, 0x1000, v78
	s_nop 1
	v_addc_co_u32_e32 v61, vcc, 0, v79, vcc
	global_load_dwordx4 v[48:51], v[52:53], off
	s_nop 0
	global_load_dwordx4 v[52:55], v[52:53], off offset:64
	s_nop 0
	global_load_dwordx4 v[56:59], v[60:61], off
	s_nop 0
	global_load_dwordx4 v[60:63], v[60:61], off offset:64
	s_nop 0
	global_load_dwordx4 v[64:67], v[88:89], off offset:128
	global_load_dwordx4 v[68:71], v[92:93], off offset:128
	v_mov_b32_e32 v110, v200
	v_mov_b32_e32 v111, v201
	v_mov_b32_e32 v116, v202
	v_mov_b32_e32 v117, v203
	v_add_co_u32_e32 v80, vcc, 0x1000, v80
	s_nop 1
	v_addc_co_u32_e32 v81, vcc, 0, v81, vcc
	v_add_co_u32_e32 v84, vcc, 0x1000, v78
	s_nop 1
	v_addc_co_u32_e32 v85, vcc, 0, v79, vcc
	global_load_dwordx4 v[72:75], v[80:81], off offset:2048
	s_nop 0
	global_load_dwordx4 v[76:79], v[80:81], off offset:2112
	s_nop 0
	global_load_dwordx4 v[80:83], v[84:85], off offset:2048
	s_nop 0
	global_load_dwordx4 v[84:87], v[84:85], off offset:2112
	s_nop 0
	global_load_dwordx4 v[88:91], v[88:89], off offset:192
	s_nop 0
	global_load_dwordx4 v[92:95], v[92:93], off offset:192
	s_waitcnt vmcnt(6)
	v_mov_b32_e32 v96, v204
	v_mov_b32_e32 v97, v205
	v_mov_b32_e32 v98, v206
	v_mov_b32_e32 v99, v207
	s_movk_i32 s0, 0x2200
	v_bfe_u32 v128, v100, 4, 2
	v_mul_f32_e32 v136, 0xc138aa3b, v96
	v_mul_lo_u32 v96, v102, s0
	v_readlane_b32 s0, v254, 23
	s_ashr_i32 s29, s28, 31
	v_and_b32_e32 v126, 63, v100
	v_lshlrev_b32_e32 v132, 2, v128
	v_mul_f32_e32 v135, 0xc138aa3b, v97
	v_add_u32_e32 v96, s0, v96
	v_mul_u32_u24_e32 v97, 0x44, v127
	s_lshl_b64 s[0:1], s[28:29], 11
	v_lshlrev_b64 v[118:119], 1, v[124:125]
	v_mul_f32_e32 v137, 0xc138aa3b, v117
	v_mul_f32_e32 v138, 0xc138aa3b, v116
	v_lshlrev_b32_e32 v97, 2, v97
	v_lshlrev_b32_e32 v120, 2, v132
	v_lshl_add_u64 v[116:117], s[0:1], 0, v[118:119]
	v_lshlrev_b32_e32 v176, 1, v126
	v_add3_u32 v154, v96, v97, v120
	v_lshl_add_u32 v155, v126, 2, v96
	v_lshl_add_u64 v[96:97], v[116:117], 0, v[176:177]
	v_lshl_add_u64 v[122:123], s[56:57], 0, v[96:97]
	v_lshlrev_b32_e32 v96, 1, v100
	v_and_b32_e32 v96, 0xffffff80, v96
	v_lshlrev_b32_e32 v133, 3, v128
	v_mad_u32_u24 v96, v127, s7, v96
	v_lshlrev_b32_e32 v97, 4, v128
	v_lshlrev_b32_e32 v121, 6, v127
	v_mul_f32_e32 v134, 0xc138aa3b, v98
	v_mul_f32_e32 v139, 0xc138aa3b, v111
	v_mul_f32_e32 v140, 0xc138aa3b, v110
	v_mul_f32_e32 v141, 0xc138aa3b, v109
	v_mul_f32_e32 v142, 0xc138aa3b, v108
	v_mul_f32_e32 v143, 0xc138aa3b, v107
	v_mul_f32_e32 v144, 0xc138aa3b, v106
	v_mul_f32_e32 v145, 0xc138aa3b, v105
	v_mul_f32_e32 v146, 0xc138aa3b, v104
	v_mul_f32_e32 v147, 0xc138aa3b, v103
	v_mul_f32_e32 v148, 0xc138aa3b, v101
	v_mul_f32_e32 v149, 0xc138aa3b, v99
	v_add3_u32 v150, v96, v97, 0
	v_add3_u32 v151, v96, v133, 0
	v_mov_b32_e32 v129, 1.0
	v_mov_b32_e32 v130, 0
	s_mov_b64 s[0:1], 0
	s_waitcnt vmcnt(0)
	s_lshl_b32 s64, s28, 11
	s_add_u32 s66, s56, s64
	s_addc_u32 s67, s57, 0
	s_add_u32 s66, s66, 0x1859000
	s_addc_u32 s67, s67, 0
	v_lshlrev_b32_e32 v220, 1, v245
	v_mul_f32_e32 v16, 0xbfb8aa3b, v16
	v_mul_f32_e32 v17, 0xbfb8aa3b, v17
	v_mul_f32_e32 v18, 0xbfb8aa3b, v18
	v_mul_f32_e32 v19, 0xbfb8aa3b, v19
	v_mul_f32_e32 v20, 0xbfb8aa3b, v20
	v_mul_f32_e32 v21, 0xbfb8aa3b, v21
	v_mul_f32_e32 v22, 0xbfb8aa3b, v22
	v_mul_f32_e32 v23, 0xbfb8aa3b, v23
	v_mul_f32_e32 v40, 0xbfb8aa3b, v40
	v_mul_f32_e32 v41, 0xbfb8aa3b, v41
	v_mul_f32_e32 v42, 0xbfb8aa3b, v42
	v_mul_f32_e32 v43, 0xbfb8aa3b, v43
	v_mul_f32_e32 v44, 0xbfb8aa3b, v44
	v_mul_f32_e32 v45, 0xbfb8aa3b, v45
	v_mul_f32_e32 v46, 0xbfb8aa3b, v46
	v_mul_f32_e32 v47, 0xbfb8aa3b, v47
	v_mul_f32_e32 v64, 0xbfb8aa3b, v64
	v_mul_f32_e32 v65, 0xbfb8aa3b, v65
	v_mul_f32_e32 v66, 0xbfb8aa3b, v66
	v_mul_f32_e32 v67, 0xbfb8aa3b, v67
	v_mul_f32_e32 v68, 0xbfb8aa3b, v68
	v_mul_f32_e32 v69, 0xbfb8aa3b, v69
	v_mul_f32_e32 v70, 0xbfb8aa3b, v70
	v_mul_f32_e32 v71, 0xbfb8aa3b, v71
	v_mul_f32_e32 v88, 0xbfb8aa3b, v88
	v_mul_f32_e32 v89, 0xbfb8aa3b, v89
	v_mul_f32_e32 v90, 0xbfb8aa3b, v90
	v_mul_f32_e32 v91, 0xbfb8aa3b, v91
	v_mul_f32_e32 v92, 0xbfb8aa3b, v92
	v_mul_f32_e32 v93, 0xbfb8aa3b, v93
	v_mul_f32_e32 v94, 0xbfb8aa3b, v94
	v_mul_f32_e32 v95, 0xbfb8aa3b, v95
; #define LAS __attribute__((address_space(3)))
; __device__ __forceinline__ float bf2f(bf16_t b) { return __uint_as_float(((unsigned)b) << 16); }
; __device__ __forceinline__ float sigmoidf_(float x) { return __builtin_amdgcn_rcpf(1.0f + __expf(-x)); }
; __device__ __forceinline__ f32x4 mfma16(bf16x8 a, bf16x8 b, f32x4 c) { return __builtin_amdgcn_mfma_f32_16x16x32_bf16(a, b, c, 0, 0, 0); }
; template <int DIR> __device__ __forceinline__ void lru_dir(const Params& p, int l, int n, int h, int lane, LAS bf16_t* XC, LAS float* STA, LAS float* STU) {
;     ...
;         f32x4 za[4], zx[4];
; #pragma unroll
;         for (int nf = 0; nf < 4; ++nf) { za[nf] = (f32x4){0.f, 0.f, 0.f, 0.f}; zx[nf] = za[nf];
;             za[nf] = mfma16(wa[nf][0], xf[0], za[nf]); za[nf] = mfma16(wa[nf][1], xf[1], za[nf]);
;             zx[nf] = mfma16(wx[nf][0], xf[0], zx[nf]); zx[nf] = mfma16(wx[nf][1], xf[1], zx[nf]); }
; #pragma unroll
;         for (int nf = 0; nf < 4; ++nf) {
;             const int jo = 16 * nf + 4 * q;
;             const bf16x4 xc4 = *(const LAS bf16x4*)(XC + (16 * mi + c) * 520 + 64 * h + jo);
;             const f32x4 zav = za[nf] + ba4[nf], zxv = zx[nf] + bx4[nf];
;             f32x4 av, uv;
; #pragma unroll
;             for (int r = 0; r < 4; ++r) {
;                 const float ra = sigmoidf_(zav[r]), ix = sigmoidf_(zxv[r]);
;                 const float la = ra * sp4[nf][r];
;                 av[r] = __expf(la);
;                 const float x2 = 2.0f * la;
;                 const float om = -x2 * (1.0f + x2 * (0.5f + x2 * (0.16666667f + x2 * (0.041666668f + x2 * (0.0083333338f + x2 * (0.0013888889f + x2 * 0.0001984127f))))));
;                 uv[r] = bf2f((bf16_t)xc4[r]) * ix * __builtin_amdgcn_sqrtf(fmaxf(om, 0.f));
;             }
;             *(LAS f32x4*)(STA + c * 68 + jo) = av; *(LAS f32x4*)(STU + c * 68 + jo) = uv;
.Llru0_loop:
	ds_read_b128 v[172:175], v150
	ds_read_b128 v[178:181], v150 offset:64
	ds_read_b64 v[182:183], v151
	ds_read_b64 v[184:185], v151 offset:32
	ds_read_b64 v[186:187], v151 offset:64
	ds_read_b64 v[188:189], v151 offset:96
	s_add_u32 s64, s66, s0
	s_addc_u32 s65, s67, 0
	s_waitcnt lgkmcnt(4)
	v_mfma_f32_16x16x32_bf16 v[156:159], v[4:7], v[172:175], 0
	v_mfma_f32_16x16x32_bf16 v[96:99], v[0:3], v[172:175], 0
	v_mfma_f32_16x16x32_bf16 v[160:163], v[24:27], v[172:175], 0
	v_mfma_f32_16x16x32_bf16 v[100:103], v[32:35], v[172:175], 0
	v_mfma_f32_16x16x32_bf16 v[164:167], v[48:51], v[172:175], 0
	v_mfma_f32_16x16x32_bf16 v[104:107], v[56:59], v[172:175], 0
	v_mfma_f32_16x16x32_bf16 v[168:171], v[72:75], v[172:175], 0
	v_mfma_f32_16x16x32_bf16 v[108:111], v[80:83], v[172:175], 0
	v_mfma_f32_16x16x32_bf16 v[156:159], v[8:11], v[178:181], v[156:159]
	v_mfma_f32_16x16x32_bf16 v[96:99], v[12:15], v[178:181], v[96:99]
	v_mfma_f32_16x16x32_bf16 v[160:163], v[28:31], v[178:181], v[160:163]
	v_mfma_f32_16x16x32_bf16 v[100:103], v[36:39], v[178:181], v[100:103]
	v_mfma_f32_16x16x32_bf16 v[164:167], v[52:55], v[178:181], v[164:167]
	v_mfma_f32_16x16x32_bf16 v[104:107], v[60:63], v[178:181], v[104:107]
	v_mfma_f32_16x16x32_bf16 v[168:171], v[76:79], v[178:181], v[168:171]
	v_mfma_f32_16x16x32_bf16 v[108:111], v[84:87], v[178:181], v[108:111]
	s_waitcnt lgkmcnt(0)
	v_lshlrev_b32_e32 v204, 16, v182
	v_and_b32_e32 v205, 0xffff0000, v182
	v_lshlrev_b32_e32 v206, 16, v183
	v_and_b32_e32 v207, 0xffff0000, v183
	v_lshlrev_b32_e32 v208, 16, v184
	v_and_b32_e32 v209, 0xffff0000, v184
	v_lshlrev_b32_e32 v210, 16, v185
	v_and_b32_e32 v211, 0xffff0000, v185
	v_lshlrev_b32_e32 v212, 16, v186
	v_and_b32_e32 v213, 0xffff0000, v186
	v_lshlrev_b32_e32 v214, 16, v187
	v_and_b32_e32 v215, 0xffff0000, v187
	v_lshlrev_b32_e32 v216, 16, v188
	v_and_b32_e32 v217, 0xffff0000, v188
	v_lshlrev_b32_e32 v218, 16, v189
	v_and_b32_e32 v219, 0xffff0000, v189
	v_fmamk_f32 v192, v156, 0xbfb8aa3b, v16
	v_fmamk_f32 v195, v157, 0xbfb8aa3b, v17
	v_fmamk_f32 v198, v158, 0xbfb8aa3b, v18
	v_fmamk_f32 v201, v159, 0xbfb8aa3b, v19
	v_fmamk_f32 v193, v96, 0xbfb8aa3b, v20
	v_fmamk_f32 v196, v97, 0xbfb8aa3b, v21
	v_fmamk_f32 v199, v98, 0xbfb8aa3b, v22
	v_fmamk_f32 v202, v99, 0xbfb8aa3b, v23
	v_exp_f32_e32 v192, v192
	v_exp_f32_e32 v195, v195
	v_exp_f32_e32 v198, v198
	v_exp_f32_e32 v201, v201
	v_exp_f32_e32 v193, v193
	v_exp_f32_e32 v196, v196
	v_exp_f32_e32 v199, v199
	v_exp_f32_e32 v202, v202
	v_add_f32_e32 v192, 1.0, v192
	v_add_f32_e32 v195, 1.0, v195
	v_add_f32_e32 v198, 1.0, v198
	v_add_f32_e32 v201, 1.0, v201
	v_add_f32_e32 v193, 1.0, v193
	v_add_f32_e32 v196, 1.0, v196
	v_add_f32_e32 v199, 1.0, v199
	v_add_f32_e32 v202, 1.0, v202
	v_rcp_f32_e32 v192, v192
	v_rcp_f32_e32 v195, v195
	v_rcp_f32_e32 v198, v198
	v_rcp_f32_e32 v201, v201
	v_rcp_f32_e32 v193, v193
	v_rcp_f32_e32 v196, v196
	v_rcp_f32_e32 v199, v199
	v_rcp_f32_e32 v202, v202
	v_mul_f32_e32 v192, v148, v192
	v_mul_f32_e32 v195, v147, v195
	v_mul_f32_e32 v198, v146, v198
	v_mul_f32_e32 v201, v145, v201
	v_exp_f32_e32 v156, v192
	v_exp_f32_e32 v157, v195
	v_exp_f32_e32 v158, v198
	v_exp_f32_e32 v159, v201
	v_fma_f32 v192, -v156, v156, 1.0
	v_fma_f32 v195, -v157, v157, 1.0
	v_fma_f32 v198, -v158, v158, 1.0
	v_fma_f32 v201, -v159, v159, 1.0
	v_max_f32_e32 v192, 0, v192
	v_max_f32_e32 v195, 0, v195
	v_max_f32_e32 v198, 0, v198
	v_max_f32_e32 v201, 0, v201
	v_sqrt_f32_e32 v192, v192
	v_sqrt_f32_e32 v195, v195
	v_sqrt_f32_e32 v198, v198
	v_sqrt_f32_e32 v201, v201
	v_mul_f32_e32 v193, v193, v204
	v_mul_f32_e32 v196, v196, v205
	v_mul_f32_e32 v199, v199, v206
	v_mul_f32_e32 v202, v202, v207
	v_mul_f32_e32 v96, v193, v192
	v_mul_f32_e32 v97, v196, v195
	v_mul_f32_e32 v98, v199, v198
	v_mul_f32_e32 v99, v202, v201
	ds_write_b128 v154, v[156:159]
	ds_write_b128 v154, v[96:99] offset:4352
	v_fmamk_f32 v192, v160, 0xbfb8aa3b, v40
	v_fmamk_f32 v195, v161, 0xbfb8aa3b, v41
	v_fmamk_f32 v198, v162, 0xbfb8aa3b, v42
	v_fmamk_f32 v201, v163, 0xbfb8aa3b, v43
	v_fmamk_f32 v193, v100, 0xbfb8aa3b, v44
	v_fmamk_f32 v196, v101, 0xbfb8aa3b, v45
	v_fmamk_f32 v199, v102, 0xbfb8aa3b, v46
	v_fmamk_f32 v202, v103, 0xbfb8aa3b, v47
	v_exp_f32_e32 v192, v192
	v_exp_f32_e32 v195, v195
	v_exp_f32_e32 v198, v198
	v_exp_f32_e32 v201, v201
	v_exp_f32_e32 v193, v193
	v_exp_f32_e32 v196, v196
	v_exp_f32_e32 v199, v199
	v_exp_f32_e32 v202, v202
	v_add_f32_e32 v192, 1.0, v192
	v_add_f32_e32 v195, 1.0, v195
	v_add_f32_e32 v198, 1.0, v198
	v_add_f32_e32 v201, 1.0, v201
	v_add_f32_e32 v193, 1.0, v193
	v_add_f32_e32 v196, 1.0, v196
	v_add_f32_e32 v199, 1.0, v199
	v_add_f32_e32 v202, 1.0, v202
	v_rcp_f32_e32 v192, v192
	v_rcp_f32_e32 v195, v195
	v_rcp_f32_e32 v198, v198
	v_rcp_f32_e32 v201, v201
	v_rcp_f32_e32 v193, v193
	v_rcp_f32_e32 v196, v196
	v_rcp_f32_e32 v199, v199
	v_rcp_f32_e32 v202, v202
	v_mul_f32_e32 v192, v144, v192
	v_mul_f32_e32 v195, v143, v195
	v_mul_f32_e32 v198, v142, v198
	v_mul_f32_e32 v201, v141, v201
	v_exp_f32_e32 v160, v192
	v_exp_f32_e32 v161, v195
	v_exp_f32_e32 v162, v198
	v_exp_f32_e32 v163, v201
	v_fma_f32 v192, -v160, v160, 1.0
	v_fma_f32 v195, -v161, v161, 1.0
	v_fma_f32 v198, -v162, v162, 1.0
	v_fma_f32 v201, -v163, v163, 1.0
	v_max_f32_e32 v192, 0, v192
	v_max_f32_e32 v195, 0, v195
	v_max_f32_e32 v198, 0, v198
	v_max_f32_e32 v201, 0, v201
	v_sqrt_f32_e32 v192, v192
	v_sqrt_f32_e32 v195, v195
	v_sqrt_f32_e32 v198, v198
	v_sqrt_f32_e32 v201, v201
	v_mul_f32_e32 v193, v193, v208
	v_mul_f32_e32 v196, v196, v209
	v_mul_f32_e32 v199, v199, v210
	v_mul_f32_e32 v202, v202, v211
	v_mul_f32_e32 v100, v193, v192
	v_mul_f32_e32 v101, v196, v195
; #define LAS __attribute__((address_space(3)))
; __device__ __forceinline__ float bf2f(bf16_t b) { return __uint_as_float(((unsigned)b) << 16); }
; __device__ __forceinline__ unsigned cvtpk(float lo, float hi) { const f32x2 v = (f32x2){lo, hi}; const bf16v2 b = __builtin_convertvector(v, bf16v2); return __builtin_bit_cast(unsigned, b); }
; __device__ __forceinline__ float sigmoidf_(float x) { return __builtin_amdgcn_rcpf(1.0f + __expf(-x)); }
; template <int DIR> __device__ __forceinline__ void lru_dir(const Params& p, int l, int n, int h, int lane, LAS bf16_t* XC, LAS float* STA, LAS float* STU) {
;     ...
;         for (int nf = 0; nf < 4; ++nf) {
;             const int jo = 16 * nf + 4 * q;
;             const bf16x4 xc4 = *(const LAS bf16x4*)(XC + (16 * mi + c) * 520 + 64 * h + jo);
;             const f32x4 zav = za[nf] + ba4[nf], zxv = zx[nf] + bx4[nf];
;             f32x4 av, uv;
; #pragma unroll
;             for (int r = 0; r < 4; ++r) {
;                 const float ra = sigmoidf_(zav[r]), ix = sigmoidf_(zxv[r]);
;                 const float la = ra * sp4[nf][r];
;                 av[r] = __expf(la);
;                 const float x2 = 2.0f * la;
;                 const float om = -x2 * (1.0f + x2 * (0.5f + x2 * (0.16666667f + x2 * (0.041666668f + x2 * (0.0083333338f + x2 * (0.0013888889f + x2 * 0.0001984127f))))));
;                 uv[r] = bf2f((bf16_t)xc4[r]) * ix * __builtin_amdgcn_sqrtf(fmaxf(om, 0.f));
;             }
;             *(LAS f32x4*)(STA + c * 68 + jo) = av; *(LAS f32x4*)(STU + c * 68 + jo) = uv;
;         }
;         LDS_FENCE();
;         float aa[16], uu[16];
; #pragma unroll
;         for (int s = 0; s < 16; ++s) { aa[s] = STA[s * 68 + j]; uu[s] = STU[s * 68 + j]; }
;         LDS_FENCE();
; #pragma unroll
;         for (int s = 0; s < 16; ++s) {
;             const int tl = DIR == 0 ? s : 15 - s;
;             hcar = aa[tl] * hcar + uu[tl]; P *= aa[tl];
;             const size_t row = (size_t)(t0 + 16 * mi + tl);
;             if (DIR == 0) { const unsigned w = cvtpk(hcar, P); y[row * D + 64 * h + j] = (bf16_t)(w & 0xffffu); y[row * D + 512 + 64 * h + j] = (bf16_t)(w >> 16); }
;             else { const unsigned w = cvtpk(bf2f(hfp[tl]) + hcar, P); y[row * D + 64 * h + j] = (bf16_t)(w & 0xffffu); __builtin_nontemporal_store((bf16_t)(w >> 16), PB + row * 512 + 64 * h + j); }
;         }
	v_mul_f32_e32 v102, v199, v198
	v_mul_f32_e32 v103, v202, v201
	ds_write_b128 v154, v[160:163] offset:64
	ds_write_b128 v154, v[100:103] offset:4416
	v_fmamk_f32 v192, v164, 0xbfb8aa3b, v64
	v_fmamk_f32 v195, v165, 0xbfb8aa3b, v65
	v_fmamk_f32 v198, v166, 0xbfb8aa3b, v66
	v_fmamk_f32 v201, v167, 0xbfb8aa3b, v67
	v_fmamk_f32 v193, v104, 0xbfb8aa3b, v68
	v_fmamk_f32 v196, v105, 0xbfb8aa3b, v69
	v_fmamk_f32 v199, v106, 0xbfb8aa3b, v70
	v_fmamk_f32 v202, v107, 0xbfb8aa3b, v71
	v_exp_f32_e32 v192, v192
	v_exp_f32_e32 v195, v195
	v_exp_f32_e32 v198, v198
	v_exp_f32_e32 v201, v201
	v_exp_f32_e32 v193, v193
	v_exp_f32_e32 v196, v196
	v_exp_f32_e32 v199, v199
	v_exp_f32_e32 v202, v202
	v_add_f32_e32 v192, 1.0, v192
	v_add_f32_e32 v195, 1.0, v195
	v_add_f32_e32 v198, 1.0, v198
	v_add_f32_e32 v201, 1.0, v201
	v_add_f32_e32 v193, 1.0, v193
	v_add_f32_e32 v196, 1.0, v196
	v_add_f32_e32 v199, 1.0, v199
	v_add_f32_e32 v202, 1.0, v202
	v_rcp_f32_e32 v192, v192
	v_rcp_f32_e32 v195, v195
	v_rcp_f32_e32 v198, v198
	v_rcp_f32_e32 v201, v201
	v_rcp_f32_e32 v193, v193
	v_rcp_f32_e32 v196, v196
	v_rcp_f32_e32 v199, v199
	v_rcp_f32_e32 v202, v202
	v_mul_f32_e32 v192, v140, v192
	v_mul_f32_e32 v195, v139, v195
	v_mul_f32_e32 v198, v138, v198
	v_mul_f32_e32 v201, v137, v201
	v_exp_f32_e32 v164, v192
	v_exp_f32_e32 v165, v195
	v_exp_f32_e32 v166, v198
	v_exp_f32_e32 v167, v201
	v_fma_f32 v192, -v164, v164, 1.0
	v_fma_f32 v195, -v165, v165, 1.0
	v_fma_f32 v198, -v166, v166, 1.0
	v_fma_f32 v201, -v167, v167, 1.0
	v_max_f32_e32 v192, 0, v192
	v_max_f32_e32 v195, 0, v195
	v_max_f32_e32 v198, 0, v198
	v_max_f32_e32 v201, 0, v201
	v_sqrt_f32_e32 v192, v192
	v_sqrt_f32_e32 v195, v195
	v_sqrt_f32_e32 v198, v198
	v_sqrt_f32_e32 v201, v201
	v_mul_f32_e32 v193, v193, v212
	v_mul_f32_e32 v196, v196, v213
	v_mul_f32_e32 v199, v199, v214
	v_mul_f32_e32 v202, v202, v215
	v_mul_f32_e32 v104, v193, v192
	v_mul_f32_e32 v105, v196, v195
	v_mul_f32_e32 v106, v199, v198
	v_mul_f32_e32 v107, v202, v201
	ds_write_b128 v154, v[164:167] offset:128
	ds_write_b128 v154, v[104:107] offset:4480
	v_fmamk_f32 v192, v168, 0xbfb8aa3b, v88
	v_fmamk_f32 v195, v169, 0xbfb8aa3b, v89
	v_fmamk_f32 v198, v170, 0xbfb8aa3b, v90
	v_fmamk_f32 v201, v171, 0xbfb8aa3b, v91
	v_fmamk_f32 v193, v108, 0xbfb8aa3b, v92
	v_fmamk_f32 v196, v109, 0xbfb8aa3b, v93
	v_fmamk_f32 v199, v110, 0xbfb8aa3b, v94
	v_fmamk_f32 v202, v111, 0xbfb8aa3b, v95
	v_exp_f32_e32 v192, v192
	v_exp_f32_e32 v195, v195
	v_exp_f32_e32 v198, v198
	v_exp_f32_e32 v201, v201
	v_exp_f32_e32 v193, v193
	v_exp_f32_e32 v196, v196
	v_exp_f32_e32 v199, v199
	v_exp_f32_e32 v202, v202
	v_add_f32_e32 v192, 1.0, v192
	v_add_f32_e32 v195, 1.0, v195
	v_add_f32_e32 v198, 1.0, v198
	v_add_f32_e32 v201, 1.0, v201
	v_add_f32_e32 v193, 1.0, v193
	v_add_f32_e32 v196, 1.0, v196
	v_add_f32_e32 v199, 1.0, v199
	v_add_f32_e32 v202, 1.0, v202
	v_rcp_f32_e32 v192, v192
	v_rcp_f32_e32 v195, v195
	v_rcp_f32_e32 v198, v198
	v_rcp_f32_e32 v201, v201
	v_rcp_f32_e32 v193, v193
	v_rcp_f32_e32 v196, v196
	v_rcp_f32_e32 v199, v199
	v_rcp_f32_e32 v202, v202
	v_mul_f32_e32 v192, v136, v192
	v_mul_f32_e32 v195, v135, v195
	v_mul_f32_e32 v198, v134, v198
	v_mul_f32_e32 v201, v149, v201
	v_exp_f32_e32 v168, v192
	v_exp_f32_e32 v169, v195
	v_exp_f32_e32 v170, v198
	v_exp_f32_e32 v171, v201
	v_fma_f32 v192, -v168, v168, 1.0
	v_fma_f32 v195, -v169, v169, 1.0
	v_fma_f32 v198, -v170, v170, 1.0
	v_fma_f32 v201, -v171, v171, 1.0
	v_max_f32_e32 v192, 0, v192
	v_max_f32_e32 v195, 0, v195
	v_max_f32_e32 v198, 0, v198
	v_max_f32_e32 v201, 0, v201
	v_sqrt_f32_e32 v192, v192
	v_sqrt_f32_e32 v195, v195
	v_sqrt_f32_e32 v198, v198
	v_sqrt_f32_e32 v201, v201
	v_mul_f32_e32 v193, v193, v216
	v_mul_f32_e32 v196, v196, v217
	v_mul_f32_e32 v199, v199, v218
	v_mul_f32_e32 v202, v202, v219
	v_mul_f32_e32 v108, v193, v192
	v_mul_f32_e32 v109, v196, v195
	v_mul_f32_e32 v110, v199, v198
	v_mul_f32_e32 v111, v202, v201
	ds_write_b128 v154, v[168:171] offset:192
	ds_write_b128 v154, v[108:111] offset:4544
	s_waitcnt lgkmcnt(0)
	ds_read_b32 v204, v155
	ds_read_b32 v172, v155 offset:4352
	ds_read_b32 v205, v155 offset:272
	ds_read_b32 v173, v155 offset:4624
	ds_read_b32 v206, v155 offset:544
	ds_read_b32 v174, v155 offset:4896
	ds_read_b32 v207, v155 offset:816
	ds_read_b32 v175, v155 offset:5168
	ds_read_b32 v208, v155 offset:1088
	ds_read_b32 v178, v155 offset:5440
	ds_read_b32 v209, v155 offset:1360
	ds_read_b32 v179, v155 offset:5712
	ds_read_b32 v210, v155 offset:1632
	ds_read_b32 v180, v155 offset:5984
	ds_read_b32 v211, v155 offset:1904
	ds_read_b32 v181, v155 offset:6256
	s_waitcnt lgkmcnt(14)
	v_fma_f32 v130, v130, v204, v172
	v_mul_f32_e32 v129, v129, v204
	v_cvt_pk_bf16_f32 v190, v130, v129
	global_store_short v220, v190, s[64:65] offset:-4096
	global_store_short_d16_hi v220, v190, s[64:65] offset:-3072
	ds_read_b32 v212, v155 offset:2176
	ds_read_b32 v182, v155 offset:6528
	s_waitcnt lgkmcnt(14)
	v_fma_f32 v130, v130, v205, v173
	v_mul_f32_e32 v129, v129, v205
	v_cvt_pk_bf16_f32 v191, v130, v129
	global_store_short v220, v191, s[64:65] offset:-2048
	global_store_short_d16_hi v220, v191, s[64:65] offset:-1024
	ds_read_b32 v213, v155 offset:2448
	ds_read_b32 v183, v155 offset:6800
	s_waitcnt lgkmcnt(14)
	v_fma_f32 v130, v130, v206, v174
	v_mul_f32_e32 v129, v129, v206
	v_cvt_pk_bf16_f32 v190, v130, v129
	global_store_short v220, v190, s[64:65] offset:0
	global_store_short_d16_hi v220, v190, s[64:65] offset:1024
	ds_read_b32 v214, v155 offset:2720
	ds_read_b32 v184, v155 offset:7072
	s_waitcnt lgkmcnt(14)
; __device__ __forceinline__ float bf2f(bf16_t b) { return __uint_as_float(((unsigned)b) << 16); }
; __device__ __forceinline__ unsigned cvtpk(float lo, float hi) { const f32x2 v = (f32x2){lo, hi}; const bf16v2 b = __builtin_convertvector(v, bf16v2); return __builtin_bit_cast(unsigned, b); }
; template <int DIR> __device__ __forceinline__ void lru_dir(const Params& p, int l, int n, int h, int lane, LAS bf16_t* XC, LAS float* STA, LAS float* STU) {
;     ...
; #pragma unroll
;         for (int s = 0; s < 16; ++s) {
;             const int tl = DIR == 0 ? s : 15 - s;
;             hcar = aa[tl] * hcar + uu[tl]; P *= aa[tl];
;             const size_t row = (size_t)(t0 + 16 * mi + tl);
;             if (DIR == 0) { const unsigned w = cvtpk(hcar, P); y[row * D + 64 * h + j] = (bf16_t)(w & 0xffffu); y[row * D + 512 + 64 * h + j] = (bf16_t)(w >> 16); }
;             else { const unsigned w = cvtpk(bf2f(hfp[tl]) + hcar, P); y[row * D + 64 * h + j] = (bf16_t)(w & 0xffffu); __builtin_nontemporal_store((bf16_t)(w >> 16), PB + row * 512 + 64 * h + j); }
;         }
	v_fma_f32 v130, v130, v207, v175
	v_mul_f32_e32 v129, v129, v207
	v_cvt_pk_bf16_f32 v191, v130, v129
	global_store_short v220, v191, s[64:65] offset:2048
	global_store_short_d16_hi v220, v191, s[64:65] offset:3072
	ds_read_b32 v215, v155 offset:2992
	ds_read_b32 v185, v155 offset:7344
	s_waitcnt lgkmcnt(14)
	v_fma_f32 v130, v130, v208, v178
	v_mul_f32_e32 v129, v129, v208
	v_cvt_pk_bf16_f32 v190, v130, v129
	s_add_u32 s64, s64, 0x2000
	s_addc_u32 s65, s65, 0
	global_store_short v220, v190, s[64:65] offset:-4096
	global_store_short_d16_hi v220, v190, s[64:65] offset:-3072
	ds_read_b32 v216, v155 offset:3264
	ds_read_b32 v186, v155 offset:7616
	s_waitcnt lgkmcnt(14)
	v_fma_f32 v130, v130, v209, v179
	v_mul_f32_e32 v129, v129, v209
	v_cvt_pk_bf16_f32 v191, v130, v129
	global_store_short v220, v191, s[64:65] offset:-2048
	global_store_short_d16_hi v220, v191, s[64:65] offset:-1024
	ds_read_b32 v217, v155 offset:3536
	ds_read_b32 v187, v155 offset:7888
	s_waitcnt lgkmcnt(14)
	v_fma_f32 v130, v130, v210, v180
	v_mul_f32_e32 v129, v129, v210
	v_cvt_pk_bf16_f32 v190, v130, v129
	global_store_short v220, v190, s[64:65] offset:0
	global_store_short_d16_hi v220, v190, s[64:65] offset:1024
	ds_read_b32 v218, v155 offset:3808
	ds_read_b32 v188, v155 offset:8160
	s_waitcnt lgkmcnt(14)
	v_fma_f32 v130, v130, v211, v181
	v_mul_f32_e32 v129, v129, v211
	v_cvt_pk_bf16_f32 v191, v130, v129
	global_store_short v220, v191, s[64:65] offset:2048
	global_store_short_d16_hi v220, v191, s[64:65] offset:3072
	ds_read_b32 v219, v155 offset:4080
	ds_read_b32 v189, v155 offset:8432
	s_waitcnt lgkmcnt(14)
	v_fma_f32 v130, v130, v212, v182
	v_mul_f32_e32 v129, v129, v212
	v_cvt_pk_bf16_f32 v190, v130, v129
	s_add_u32 s64, s64, 0x2000
	s_addc_u32 s65, s65, 0
	global_store_short v220, v190, s[64:65] offset:-4096
	global_store_short_d16_hi v220, v190, s[64:65] offset:-3072
	s_waitcnt lgkmcnt(12)
	v_fma_f32 v130, v130, v213, v183
	v_mul_f32_e32 v129, v129, v213
	v_cvt_pk_bf16_f32 v191, v130, v129
	global_store_short v220, v191, s[64:65] offset:-2048
	global_store_short_d16_hi v220, v191, s[64:65] offset:-1024
	s_waitcnt lgkmcnt(10)
	v_fma_f32 v130, v130, v214, v184
	v_mul_f32_e32 v129, v129, v214
	v_cvt_pk_bf16_f32 v190, v130, v129
	global_store_short v220, v190, s[64:65] offset:0
	global_store_short_d16_hi v220, v190, s[64:65] offset:1024
	s_waitcnt lgkmcnt(8)
	v_fma_f32 v130, v130, v215, v185
	v_mul_f32_e32 v129, v129, v215
	v_cvt_pk_bf16_f32 v191, v130, v129
	global_store_short v220, v191, s[64:65] offset:2048
	global_store_short_d16_hi v220, v191, s[64:65] offset:3072
	s_waitcnt lgkmcnt(6)
	v_fma_f32 v130, v130, v216, v186
	v_mul_f32_e32 v129, v129, v216
	v_cvt_pk_bf16_f32 v190, v130, v129
	s_add_u32 s64, s64, 0x2000
	s_addc_u32 s65, s65, 0
	global_store_short v220, v190, s[64:65] offset:-4096
	global_store_short_d16_hi v220, v190, s[64:65] offset:-3072
	s_waitcnt lgkmcnt(4)
	v_fma_f32 v130, v130, v217, v187
	v_mul_f32_e32 v129, v129, v217
	v_cvt_pk_bf16_f32 v191, v130, v129
	global_store_short v220, v191, s[64:65] offset:-2048
	global_store_short_d16_hi v220, v191, s[64:65] offset:-1024
	s_waitcnt lgkmcnt(2)
	v_fma_f32 v130, v130, v218, v188
	v_mul_f32_e32 v129, v129, v218
	v_cvt_pk_bf16_f32 v190, v130, v129
	global_store_short v220, v190, s[64:65] offset:0
	global_store_short_d16_hi v220, v190, s[64:65] offset:1024
	s_waitcnt lgkmcnt(0)
	v_fma_f32 v130, v130, v219, v189
	v_mul_f32_e32 v129, v129, v219
	v_cvt_pk_bf16_f32 v191, v130, v129
	global_store_short v220, v191, s[64:65] offset:2048
	global_store_short_d16_hi v220, v191, s[64:65] offset:3072
	s_add_u32 s0, s0, 0x8000
	s_addc_u32 s1, s1, 0
	v_add_u32_e32 v150, 0x4100, v150
	v_add_u32_e32 v151, 0x4100, v151
	s_cmp_lg_u32 s0, 0x20000
	s_cbranch_scc1 .Llru0_loop
; template <int DIR> __device__ __forceinline__ void lru_dir(const Params& p, int l, int n, int h, int lane, LAS bf16_t* XC, LAS float* STA, LAS float* STU) {
;     ...
;     const float* lam = p.in[10] + (size_t)(l * 2 + DIR) * 512 + 64 * h; const float* b_a = p.in[7] + (size_t)(l * 2 + DIR) * 512 + 64 * h; const float* b_x = p.in[9] + (size_t)(l * 2 + DIR) * 512 + 64 * h;
;     const bf16_t* LWa = LW + ((size_t)(DIR * 2 + 0) * 8 + h) * 4096 + c * 64 + 8 * q; const bf16_t* LWx = LW + ((size_t)(DIR * 2 + 1) * 8 + h) * 4096 + c * 64 + 8 * q;
;     bf16x8 wa[4][2], wx[4][2]; f32x4 sp4[4], ba4[4], bx4[4];
; #pragma unroll
;     for (int nf = 0; nf < 4; ++nf) {
; #pragma unroll
;         for (int ks = 0; ks < 2; ++ks) { wa[nf][ks] = *(const bf16x8*)(LWa + nf * 1024 + 32 * ks); wx[nf][ks] = *(const bf16x8*)(LWx + nf * 1024 + 32 * ks); }
;         const f32x4 lam4 = *(const f32x4*)(lam + 16 * nf + 4 * q); ba4[nf] = *(const f32x4*)(b_a + 16 * nf + 4 * q); bx4[nf] = *(const f32x4*)(b_x + 16 * nf + 4 * q);
; #pragma unroll
;         for (int r = 0; r < 4; ++r) { const float e = __expf(-lam4[r]); const float l1p = e < 0.05f ? e * (1.0f - e * (0.5f - e * (0.33333334f - e * 0.25f))) : __logf(1.0f + e); sp4[nf][r] = -8.0f * l1p; }
;     }
;     ...
;     Aprod[(size_t)(DIR * NCH + n) * 512 + 64 * h + j] = P; Hend[(size_t)(DIR * NCH + n) * 512 + 64 * h + j] = hcar;
	v_add_u32_e32 v156, 0x1000, v155
	v_add_u32_e32 v157, 0x1200, v155
	v_add_u32_e32 v158, 0x400, v155
	v_add_u32_e32 v159, 0x1400, v155
	v_add_u32_e32 v160, 0x1600, v155
	v_add_u32_e32 v161, 0x800, v155
	v_add_u32_e32 v162, 0x1800, v155
	v_add_u32_e32 v163, 0x1a00, v155
	v_add_u32_e32 v164, 0xc00, v155
	v_add_u32_e32 v165, 0x1c00, v155
	v_add_u32_e32 v166, 0x1e00, v155
	s_ashr_i32 s5, s4, 31
	s_lshl_b64 s[0:1], s[4:5], 9
	v_lshl_add_u64 v[0:1], s[0:1], 0, v[124:125]
	v_or_b32_e32 v0, v0, v126
	v_readlane_b32 s0, v254, 11
	v_lshlrev_b64 v[0:1], 2, v[0:1]
	v_readlane_b32 s1, v254, 12
	v_lshlrev_b32_e32 v6, 1, v121
	v_mov_b32_e32 v7, v177
	v_lshl_add_u64 v[2:3], s[0:1], 0, v[0:1]
	v_readlane_b32 s0, v254, 13
	v_readlane_b32 s1, v254, 14
	v_lshlrev_b32_e32 v8, 1, v133
	v_mov_b32_e32 v9, v177
	v_lshl_add_u64 v[6:7], v[114:115], 0, v[6:7]
	v_lshl_add_u64 v[0:1], s[0:1], 0, v[0:1]
	v_lshl_add_u64 v[6:7], v[6:7], 0, v[8:9]
	s_mov_b64 s[0:1], 0x20000
	v_lshl_add_u64 v[80:81], v[6:7], 0, s[0:1]
	s_mov_b64 s[0:1], 0x30000
	global_store_dword v[0:1], v130, off
	v_lshl_add_u64 v[0:1], s[22:23], 0, v[112:113]
	v_lshl_add_u64 v[78:79], v[6:7], 0, s[0:1]
	v_mov_b32_e32 v121, v177
	s_mov_b32 s0, 0x20000
	v_lshl_add_u64 v[76:77], v[0:1], 0, v[120:121]
	v_add_co_u32_e32 v0, vcc, s0, v6
	v_lshl_add_u64 v[4:5], s[38:39], 0, v[112:113]
	s_nop 0
	v_addc_co_u32_e32 v1, vcc, 0, v7, vcc
	v_lshl_add_u64 v[92:93], v[4:5], 0, v[120:121]
	v_add_co_u32_e32 v4, vcc, 0x30000, v6
	global_store_dword v[2:3], v129, off
	v_lshl_add_u64 v[2:3], s[26:27], 0, v[112:113]
	v_addc_co_u32_e32 v5, vcc, 0, v7, vcc
	v_lshl_add_u64 v[88:89], v[2:3], 0, v[120:121]
	v_readlane_b32 s0, v255, 0
	v_readlane_b32 s1, v255, 1
	v_readlane_b32 s30, v254, 47
	v_readlane_b32 s31, v254, 48
	s_add_u32 s0, s0, 0x4000
	s_addc_u32 s1, s1, 0
	s_sub_u32 s0, s0, s30
	s_subb_u32 s1, s1, s31
	v_lshl_add_u64 v[76:77], v[76:77], 0, s[0:1]
	global_load_dwordx4 v[192:195], v[76:77], off
	global_load_dwordx4 v[196:199], v[76:77], off offset:64
	global_load_dwordx4 v[200:203], v[76:77], off offset:128
	global_load_dwordx4 v[204:207], v[76:77], off offset:192
	s_nop 0
	global_load_dwordx4 v[0:3], v[0:1], off
	s_nop 0
	global_load_dwordx4 v[4:7], v[4:5], off
	s_nop 0
	global_load_dwordx4 v[8:11], v[80:81], off offset:64
	global_load_dwordx4 v[12:15], v[78:79], off offset:64
	global_load_dwordx4 v[16:19], v[88:89], off
	global_load_dwordx4 v[20:23], v[92:93], off
	s_waitcnt vmcnt(6)
	v_mov_b32_e32 v100, v192
	v_mov_b32_e32 v101, v193
	v_mov_b32_e32 v102, v194
	v_mov_b32_e32 v103, v195
	global_load_dwordx4 v[24:27], v[80:81], off offset:2048
	global_load_dwordx4 v[28:31], v[80:81], off offset:2112
	global_load_dwordx4 v[32:35], v[78:79], off offset:2048
	global_load_dwordx4 v[36:39], v[78:79], off offset:2112
	global_load_dwordx4 v[40:43], v[88:89], off offset:64
	global_load_dwordx4 v[44:47], v[92:93], off offset:64
	v_mov_b32_e32 v104, v196
	v_mov_b32_e32 v105, v197
	v_mov_b32_e32 v106, v198
	v_mov_b32_e32 v107, v199
	v_add_co_u32_e32 v52, vcc, 0x1000, v80
	s_nop 1
	v_addc_co_u32_e32 v53, vcc, 0, v81, vcc
	v_add_co_u32_e32 v60, vcc, 0x1000, v78
	s_nop 1
	v_addc_co_u32_e32 v61, vcc, 0, v79, vcc
	global_load_dwordx4 v[48:51], v[52:53], off
	s_nop 0
	global_load_dwordx4 v[52:55], v[52:53], off offset:64
	s_nop 0
	global_load_dwordx4 v[56:59], v[60:61], off
	s_nop 0
	global_load_dwordx4 v[60:63], v[60:61], off offset:64
	s_nop 0
	global_load_dwordx4 v[64:67], v[88:89], off offset:128
	global_load_dwordx4 v[68:71], v[92:93], off offset:128
	v_mov_b32_e32 v108, v200
	v_mov_b32_e32 v109, v201
	v_mov_b32_e32 v110, v202
	v_mov_b32_e32 v111, v203
	v_add_co_u32_e32 v80, vcc, 0x1000, v80
	s_nop 1
	v_addc_co_u32_e32 v81, vcc, 0, v81, vcc
	v_add_co_u32_e32 v84, vcc, 0x1000, v78
	s_nop 1
	v_addc_co_u32_e32 v85, vcc, 0, v79, vcc
	global_load_dwordx4 v[72:75], v[80:81], off offset:2048
	s_nop 0
	global_load_dwordx4 v[76:79], v[80:81], off offset:2112
	s_nop 0
	global_load_dwordx4 v[80:83], v[84:85], off offset:2048
	s_nop 0
	global_load_dwordx4 v[84:87], v[84:85], off offset:2112
	s_nop 0
	global_load_dwordx4 v[88:91], v[88:89], off offset:192
	s_nop 0
	global_load_dwordx4 v[92:95], v[92:93], off offset:192
	s_waitcnt vmcnt(6)
	v_mov_b32_e32 v96, v204
	v_mov_b32_e32 v97, v205
	v_mov_b32_e32 v98, v206
	v_mov_b32_e32 v99, v207
	s_lshl_b64 s[0:1], s[28:29], 10
	s_add_u32 s0, s56, s0
	v_mul_f32_e32 v169, 0xc138aa3b, v96
	v_lshl_add_u32 v96, v124, 1, 0
	s_addc_u32 s1, s57, s1
	v_mul_f32_e32 v167, 0xc138aa3b, v98
	v_mul_f32_e32 v168, 0xc138aa3b, v97
	v_mul_f32_e32 v170, 0xc138aa3b, v111
	v_mul_f32_e32 v171, 0xc138aa3b, v110
	v_mul_f32_e32 v172, 0xc138aa3b, v109
	v_mul_f32_e32 v173, 0xc138aa3b, v108
	v_mul_f32_e32 v174, 0xc138aa3b, v107
	v_mul_f32_e32 v175, 0xc138aa3b, v106
	v_mul_f32_e32 v182, 0xc138aa3b, v105
	v_mul_f32_e32 v183, 0xc138aa3b, v104
	v_mul_f32_e32 v184, 0xc138aa3b, v103
	v_mul_f32_e32 v185, 0xc138aa3b, v102
	v_mul_f32_e32 v186, 0xc138aa3b, v101
	v_mul_f32_e32 v187, 0xc138aa3b, v100
	v_lshl_add_u32 v188, v133, 1, v96
	v_mul_f32_e32 v190, 0xc138aa3b, v99
	v_lshl_add_u32 v191, v132, 1, v96
	v_lshl_add_u64 v[128:129], s[0:1], 0, v[118:119]
	v_lshl_add_u64 v[130:131], s[56:57], 0, v[116:117]
	v_mov_b32_e32 v135, 1.0
	v_mov_b32_e32 v132, 0
	s_mov_b32 s0, 48

; __device__ __forceinline__ f32x4 mfma16(bf16x8 a, bf16x8 b, f32x4 c) { return __builtin_amdgcn_mfma_f32_16x16x32_bf16(a, b, c, 0, 0, 0); }
; template <int MODE> __device__ void mixer_gla(const Params& p, int l, int n, LAS unsigned char* lds) {
;     ...
;             for (int ef = 0; ef < 4; ++ef) { gwf[ef] = *(const bf16x8*)(GW + (size_t)(dir * 256 + 64 * h + SIGC(ef, c)) * 32 + 8 * q); bgv[ef] = p.in[13][(size_t)(l * 2 + dir) * 256 + 64 * h + SIGC(ef, c)]; }
; #pragma unroll
;             for (int ef = 0; ef < 4; ++ef) { tot[ef] = 0.f;
; #pragma unroll
;                 for (int ks = 0; ks < 2; ++ks) { f32x4 la2[2];
; #pragma unroll
;                     for (int t2 = 0; t2 < 2; ++t2) { const f32x4 z = mfma16(lrf[2 * ks + t2], gwf[ef], zero4);
; #pragma unroll
;                         for (int r = 0; r < 4; ++r) { const float zz = z[r] + bgv[ef]; const float la = (fminf(zz, 0.f) - __logf(1.0f + __expf(-fabsf(zz)))) * (1.0f / 16.0f); la2[t2][r] = la; tot[ef] += la; } }
;                     laop[ef][ks] = pack8(la2[0], la2[1]); __builtin_amdgcn_sched_barrier(0); } }
;     ...
;             for (int ef = 0; ef < 4; ++ef) { float tt = tot[ef]; tt += __shfl_xor(tt, 16); tt += __shfl_xor(tt, 32);
;                 if (vh == 0 && q == 0) dec[((size_t)(dir * NCH + n) * 4 + h) * 64 + SIGC(ef, c)] = __expf(tt); }
.LBB0_338:
	s_or_b64 exec, exec, s[0:1]
	s_lshl_b32 s4, s5, 8
	v_add_u32_e32 v30, s4, v88
	v_or_b32_e32 v16, v30, v90
	v_ashrrev_i32_e32 v17, 31, v16
	v_lshlrev_b64 v[16:17], 6, v[16:17]
	v_lshl_add_u64 v[16:17], v[92:93], 0, v[16:17]
	s_or_b32 s0, s5, s13
	global_load_dwordx4 v[24:27], v[16:17], off
	s_ashr_i32 s1, s0, 31
	s_lshl_b64 s[0:1], s[0:1], 10
	v_lshl_add_u64 v[28:29], v[114:115], 0, s[0:1]
	global_load_dword v40, v[28:29], off
	v_or_b32_e32 v16, v30, v117
	v_or_b32_e32 v20, v30, v118
	v_or_b32_e32 v30, v30, v119
	v_ashrrev_i32_e32 v17, 31, v16
	v_ashrrev_i32_e32 v21, 31, v20
	v_ashrrev_i32_e32 v31, 31, v30
	v_lshlrev_b64 v[16:17], 6, v[16:17]
	v_lshlrev_b64 v[20:21], 6, v[20:21]
	v_lshlrev_b64 v[30:31], 6, v[30:31]
	v_lshl_add_u64 v[16:17], v[92:93], 0, v[16:17]
	v_lshl_add_u64 v[20:21], v[92:93], 0, v[20:21]
	v_lshl_add_u64 v[30:31], v[92:93], 0, v[30:31]
	global_load_dwordx4 v[16:19], v[16:17], off
	s_nop 0
	global_load_dword v78, v[28:29], off offset:16
	s_nop 0
	global_load_dwordx4 v[20:23], v[20:21], off
	s_nop 0
	global_load_dword v77, v[28:29], off offset:128
	global_load_dwordx4 v[44:47], v[30:31], off
	global_load_dword v76, v[28:29], off offset:144
	s_waitcnt vmcnt(7)
	v_mfma_f32_16x16x32_bf16 v[28:31], v[12:15], v[24:27], 0
	s_waitcnt vmcnt(6)
	s_nop 6
	v_add_f32_e32 v41, v40, v28
	v_add_f32_e32 v43, v40, v29
	v_min_f32_e32 v28, 0, v41
	v_min_f32_e32 v29, 0, v43
	v_mul_f32_e64 v41, |v41|, s33
	v_mul_f32_e64 v43, |v43|, s33
	v_exp_f32_e32 v41, v41
	v_exp_f32_e32 v43, v43
	v_mul_f32_e32 v28, s50, v28
	v_mul_f32_e32 v29, s50, v29
	v_add_f32_e32 v41, 1.0, v41
	v_add_f32_e32 v43, 1.0, v43
	v_log_f32_e32 v41, v41
	v_log_f32_e32 v43, v43
	v_fmamk_f32 v68, v41, 0xbd317218, v28
	v_fmamk_f32 v69, v43, 0xbd317218, v29
	v_add_f32_e32 v31, v40, v31
	v_add_f32_e32 v29, v40, v30
	v_add_f32_e32 v28, 0, v68
	v_add_f32_e32 v41, v69, v28
	v_min_f32_e32 v28, 0, v29
	v_min_f32_e32 v30, 0, v31
	v_mul_f32_e64 v29, |v29|, s33
	v_mul_f32_e64 v31, |v31|, s33
	v_exp_f32_e32 v29, v29
	v_exp_f32_e32 v31, v31
	v_mul_f32_e32 v28, s50, v28
	v_mul_f32_e32 v30, s50, v30
	v_add_f32_e32 v29, 1.0, v29
	v_add_f32_e32 v31, 1.0, v31
	v_log_f32_e32 v29, v29
	v_log_f32_e32 v31, v31
	v_fmamk_f32 v70, v29, 0xbd317218, v28
	v_fmamk_f32 v71, v31, 0xbd317218, v30
	s_nop 0
	v_add_f32_e32 v28, v70, v41
	v_add_f32_e32 v41, v71, v28
	v_mfma_f32_16x16x32_bf16 v[28:31], v[8:11], v[24:27], 0
	s_nop 7
	v_add_f32_e32 v42, v40, v28
	v_add_f32_e32 v48, v40, v29
	v_min_f32_e32 v28, 0, v42
	v_min_f32_e32 v29, 0, v48
	v_mul_f32_e64 v42, |v42|, s33
	v_mul_f32_e64 v48, |v48|, s33
	v_exp_f32_e32 v42, v42
	v_exp_f32_e32 v48, v48
	v_mul_f32_e32 v28, s50, v28
	v_mul_f32_e32 v29, s50, v29
	v_add_f32_e32 v42, 1.0, v42
	v_add_f32_e32 v48, 1.0, v48
	v_log_f32_e32 v42, v42
	v_log_f32_e32 v48, v48
	v_fmamk_f32 v72, v42, 0xbd317218, v28
	v_fmamk_f32 v73, v48, 0xbd317218, v29
	v_add_f32_e32 v31, v40, v31
	v_add_f32_e32 v29, v40, v30
	v_add_f32_e32 v28, v72, v41
	v_add_f32_e32 v41, v73, v28
	v_min_f32_e32 v28, 0, v29
	v_min_f32_e32 v30, 0, v31
	v_mul_f32_e64 v29, |v29|, s33
	v_mul_f32_e64 v31, |v31|, s33
	v_exp_f32_e32 v29, v29
	v_exp_f32_e32 v31, v31
	v_mul_f32_e32 v28, s50, v28
	v_mul_f32_e32 v30, s50, v30
	v_add_f32_e32 v29, 1.0, v29
	v_add_f32_e32 v31, 1.0, v31
	v_log_f32_e32 v29, v29
	v_log_f32_e32 v31, v31
	v_fmamk_f32 v74, v29, 0xbd317218, v28
	v_fmamk_f32 v75, v31, 0xbd317218, v30
	s_nop 0
	v_add_f32_e32 v28, v74, v41
	v_add_f32_e32 v41, v75, v28
	v_mfma_f32_16x16x32_bf16 v[28:31], v[36:39], v[24:27], 0
	v_mfma_f32_16x16x32_bf16 v[24:27], v[32:35], v[24:27], 0
	s_nop 6
	v_add_f32_e32 v42, v40, v28
	v_add_f32_e32 v48, v40, v29
	v_min_f32_e32 v28, 0, v42
	v_min_f32_e32 v29, 0, v48
	v_mul_f32_e64 v42, |v42|, s33
	v_mul_f32_e64 v48, |v48|, s33
	v_exp_f32_e32 v42, v42
	v_exp_f32_e32 v48, v48
	v_mul_f32_e32 v28, s50, v28
	v_mul_f32_e32 v29, s50, v29
	v_add_f32_e32 v42, 1.0, v42
	v_add_f32_e32 v48, 1.0, v48
	v_log_f32_e32 v42, v42
	v_log_f32_e32 v48, v48
	v_fmamk_f32 v80, v42, 0xbd317218, v28
	v_fmamk_f32 v81, v48, 0xbd317218, v29
	v_add_f32_e32 v31, v40, v31
	v_add_f32_e32 v27, v40, v27
	v_add_f32_e32 v29, v40, v30
	v_add_f32_e32 v28, v80, v41
	v_add_f32_e32 v41, v81, v28
	v_min_f32_e32 v28, 0, v29
	v_min_f32_e32 v30, 0, v31
	v_mul_f32_e64 v29, |v29|, s33
	v_mul_f32_e64 v31, |v31|, s33
	v_exp_f32_e32 v29, v29
	v_exp_f32_e32 v31, v31
	v_mul_f32_e32 v28, s50, v28
	v_mul_f32_e32 v30, s50, v30
	v_add_f32_e32 v29, 1.0, v29
	v_add_f32_e32 v31, 1.0, v31
	v_log_f32_e32 v29, v29
	v_log_f32_e32 v31, v31
	v_fmamk_f32 v82, v29, 0xbd317218, v28
	v_fmamk_f32 v83, v31, 0xbd317218, v30
	s_nop 0
	v_add_f32_e32 v28, v82, v41
	v_add_f32_e32 v30, v83, v28
	v_add_f32_e32 v28, v40, v24
	v_add_f32_e32 v31, v40, v25
	v_min_f32_e32 v24, 0, v28
	v_min_f32_e32 v25, 0, v31
	v_mul_f32_e64 v28, |v28|, s33
	v_mul_f32_e64 v31, |v31|, s33
	v_exp_f32_e32 v28, v28
	v_exp_f32_e32 v31, v31
	v_mul_f32_e32 v24, s50, v24
	v_mul_f32_e32 v25, s50, v25
	v_add_f32_e32 v28, 1.0, v28
	v_add_f32_e32 v31, 1.0, v31
	v_log_f32_e32 v28, v28
	v_log_f32_e32 v31, v31
	v_fmamk_f32 v84, v28, 0xbd317218, v24
	v_fmamk_f32 v85, v31, 0xbd317218, v25
	v_add_f32_e32 v25, v40, v26
	v_add_f32_e32 v24, v84, v30
	v_add_f32_e32 v28, v85, v24
	v_min_f32_e32 v24, 0, v25
	v_min_f32_e32 v26, 0, v27
	v_mul_f32_e64 v25, |v25|, s33
	v_mul_f32_e64 v27, |v27|, s33
	v_exp_f32_e32 v25, v25
	v_exp_f32_e32 v27, v27
	v_mul_f32_e32 v24, s50, v24
	v_mul_f32_e32 v26, s50, v26
	v_add_f32_e32 v25, 1.0, v25
	v_add_f32_e32 v27, 1.0, v27
	v_log_f32_e32 v25, v25
	v_log_f32_e32 v27, v27
	v_fmamk_f32 v86, v25, 0xbd317218, v24
	v_fmamk_f32 v87, v27, 0xbd317218, v26
	s_nop 0
	v_add_f32_e32 v24, v86, v28
	v_add_f32_e32 v79, v87, v24
	s_waitcnt vmcnt(5)
	v_mfma_f32_16x16x32_bf16 v[64:67], v[12:15], v[16:19], 0
	v_mfma_f32_16x16x32_bf16 v[60:63], v[8:11], v[16:19], 0
	v_mfma_f32_16x16x32_bf16 v[56:59], v[36:39], v[16:19], 0
	v_mfma_f32_16x16x32_bf16 v[52:55], v[32:35], v[16:19], 0
	s_waitcnt vmcnt(3)
	v_mfma_f32_16x16x32_bf16 v[48:51], v[12:15], v[20:23], 0
	v_mfma_f32_16x16x32_bf16 v[40:43], v[8:11], v[20:23], 0
	v_mfma_f32_16x16x32_bf16 v[28:31], v[36:39], v[20:23], 0
	v_mfma_f32_16x16x32_bf16 v[24:27], v[32:35], v[20:23], 0
	s_waitcnt vmcnt(1)
	v_mfma_f32_16x16x32_bf16 v[20:23], v[12:15], v[44:47], 0
	v_mfma_f32_16x16x32_bf16 v[16:19], v[8:11], v[44:47], 0
	v_mfma_f32_16x16x32_bf16 v[12:15], v[36:39], v[44:47], 0
	v_mfma_f32_16x16x32_bf16 v[8:11], v[32:35], v[44:47], 0
	ds_bpermute_b32 v32, v91, v79
	s_add_i32 s8, s4, s12
	s_ashr_i32 s9, s8, 31
	s_lshl_b64 s[0:1], s[8:9], 10
	v_lshlrev_b32_e32 v176, 2, v90
	s_waitcnt lgkmcnt(0)
	v_add_f32_e32 v34, v79, v32
	ds_bpermute_b32 v35, v116, v34
	v_lshl_add_u64 v[32:33], v[94:95], 0, s[0:1]
	s_and_saveexec_b64 s[0:1], s[40:41]
	s_cbranch_execz .LBB0_340
	s_waitcnt lgkmcnt(0)
	v_add_f32_e32 v34, v34, v35
	v_mul_f32_e32 v34, 0x3fb8aa3b, v34
	v_exp_f32_e32 v36, v34
	v_lshl_add_u64 v[34:35], v[32:33], 0, v[176:177]
	global_store_dword v[34:35], v36, off
; __device__ __forceinline__ f32x4 mfma16(bf16x8 a, bf16x8 b, f32x4 c) { return __builtin_amdgcn_mfma_f32_16x16x32_bf16(a, b, c, 0, 0, 0); }
; template <int MODE> __device__ void mixer_gla(const Params& p, int l, int n, LAS unsigned char* lds) {
;     ...
;             for (int ef = 0; ef < 4; ++ef) { tot[ef] = 0.f;
; #pragma unroll
;                 for (int ks = 0; ks < 2; ++ks) { f32x4 la2[2];
; #pragma unroll
;                     for (int t2 = 0; t2 < 2; ++t2) { const f32x4 z = mfma16(lrf[2 * ks + t2], gwf[ef], zero4);
; #pragma unroll
;                         for (int r = 0; r < 4; ++r) { const float zz = z[r] + bgv[ef]; const float la = (fminf(zz, 0.f) - __logf(1.0f + __expf(-fabsf(zz)))) * (1.0f / 16.0f); la2[t2][r] = la; tot[ef] += la; } }
;                     laop[ef][ks] = pack8(la2[0], la2[1]); __builtin_amdgcn_sched_barrier(0); } }
;     ...
;             for (int ef = 0; ef < 4; ++ef) { float tt = tot[ef]; tt += __shfl_xor(tt, 16); tt += __shfl_xor(tt, 32);
;                 if (vh == 0 && q == 0) dec[((size_t)(dir * NCH + n) * 4 + h) * 64 + SIGC(ef, c)] = __expf(tt); }
.LBB0_340:
	s_or_b64 exec, exec, s[0:1]
	s_waitcnt lgkmcnt(0)
	v_add_f32_e32 v35, v78, v64
	v_add_f32_e32 v38, v78, v65
	v_min_f32_e32 v34, 0, v35
	v_min_f32_e32 v36, 0, v38
	v_mul_f32_e64 v35, |v35|, s33
	v_mul_f32_e64 v38, |v38|, s33
	v_exp_f32_e32 v35, v35
	v_exp_f32_e32 v38, v38
	v_mul_f32_e32 v34, s50, v34
	v_mul_f32_e32 v36, s50, v36
	v_add_f32_e32 v35, 1.0, v35
	v_add_f32_e32 v38, 1.0, v38
	v_log_f32_e32 v35, v35
	v_log_f32_e32 v38, v38
	v_fmamk_f32 v34, v35, 0xbd317218, v34
	v_fmamk_f32 v35, v38, 0xbd317218, v36
	v_add_f32_e32 v39, v78, v67
	v_add_f32_e32 v57, v78, v57
	v_add_f32_e32 v59, v78, v59
	v_add_f32_e32 v55, v78, v55
	v_add_f32_e32 v37, v78, v66
	s_nop 0
	v_add_f32_e32 v36, 0, v34
	v_add_f32_e32 v44, v35, v36
	v_min_f32_e32 v36, 0, v37
	v_min_f32_e32 v38, 0, v39
	v_mul_f32_e64 v37, |v37|, s33
	v_mul_f32_e64 v39, |v39|, s33
	v_exp_f32_e32 v37, v37
	v_exp_f32_e32 v39, v39
	v_mul_f32_e32 v36, s50, v36
	v_mul_f32_e32 v38, s50, v38
	v_add_f32_e32 v37, 1.0, v37
	v_add_f32_e32 v39, 1.0, v39
	v_log_f32_e32 v37, v37
	v_log_f32_e32 v39, v39
	v_fmamk_f32 v36, v37, 0xbd317218, v36
	v_fmamk_f32 v37, v39, 0xbd317218, v38
	v_add_f32_e32 v39, v78, v60
	v_add_f32_e32 v45, v78, v61
	v_add_f32_e32 v38, v36, v44
	v_add_f32_e32 v46, v37, v38
	v_min_f32_e32 v38, 0, v39
	v_min_f32_e32 v44, 0, v45
	v_mul_f32_e64 v39, |v39|, s33
	v_mul_f32_e64 v45, |v45|, s33
	v_exp_f32_e32 v39, v39
	v_exp_f32_e32 v45, v45
	v_mul_f32_e32 v38, s50, v38
	v_mul_f32_e32 v44, s50, v44
	v_add_f32_e32 v39, 1.0, v39
	v_add_f32_e32 v45, 1.0, v45
	v_log_f32_e32 v39, v39
	v_log_f32_e32 v45, v45
	v_fmamk_f32 v38, v39, 0xbd317218, v38
	v_fmamk_f32 v39, v45, 0xbd317218, v44
	v_add_f32_e32 v45, v78, v62
	v_add_f32_e32 v47, v78, v63
	v_add_f32_e32 v44, v38, v46
	v_add_f32_e32 v60, v39, v44
	v_min_f32_e32 v44, 0, v45
	v_min_f32_e32 v46, 0, v47
	v_mul_f32_e64 v45, |v45|, s33
	v_mul_f32_e64 v47, |v47|, s33
	v_exp_f32_e32 v45, v45
	v_exp_f32_e32 v47, v47
	v_mul_f32_e32 v44, s50, v44
	v_mul_f32_e32 v46, s50, v46
	v_add_f32_e32 v45, 1.0, v45
	v_add_f32_e32 v47, 1.0, v47
	v_log_f32_e32 v45, v45
	v_log_f32_e32 v47, v47
	v_fmamk_f32 v44, v45, 0xbd317218, v44
	v_fmamk_f32 v45, v47, 0xbd317218, v46
	v_add_f32_e32 v47, v78, v56
	s_nop 0
	v_add_f32_e32 v46, v44, v60
	v_add_f32_e32 v60, v45, v46
	v_min_f32_e32 v46, 0, v47
	v_min_f32_e32 v56, 0, v57
	v_mul_f32_e64 v47, |v47|, s33
	v_mul_f32_e64 v57, |v57|, s33
	v_exp_f32_e32 v47, v47
	v_exp_f32_e32 v57, v57
	v_mul_f32_e32 v46, s50, v46
	v_mul_f32_e32 v56, s50, v56
	v_add_f32_e32 v47, 1.0, v47
	v_add_f32_e32 v57, 1.0, v57
	v_log_f32_e32 v47, v47
	v_log_f32_e32 v57, v57
	v_fmamk_f32 v46, v47, 0xbd317218, v46
	v_fmamk_f32 v47, v57, 0xbd317218, v56
	v_add_f32_e32 v57, v78, v58
	s_nop 0
	v_add_f32_e32 v56, v46, v60
	v_add_f32_e32 v60, v47, v56
	v_min_f32_e32 v56, 0, v57
	v_min_f32_e32 v58, 0, v59
	v_mul_f32_e64 v57, |v57|, s33
	v_mul_f32_e64 v59, |v59|, s33
	v_exp_f32_e32 v57, v57
	v_exp_f32_e32 v59, v59
	v_mul_f32_e32 v56, s50, v56
	v_mul_f32_e32 v58, s50, v58
	v_add_f32_e32 v57, 1.0, v57
	v_add_f32_e32 v59, 1.0, v59
	v_log_f32_e32 v57, v57
	v_log_f32_e32 v59, v59
	v_fmamk_f32 v56, v57, 0xbd317218, v56
	v_fmamk_f32 v57, v59, 0xbd317218, v58
	s_nop 0
	v_add_f32_e32 v58, v56, v60
	v_add_f32_e32 v60, v57, v58
	v_add_f32_e32 v58, v78, v52
	v_add_f32_e32 v61, v78, v53
	v_min_f32_e32 v52, 0, v58
	v_min_f32_e32 v53, 0, v61
	v_mul_f32_e64 v58, |v58|, s33
	v_mul_f32_e64 v61, |v61|, s33
	v_exp_f32_e32 v58, v58
	v_exp_f32_e32 v61, v61
	v_mul_f32_e32 v52, s50, v52
	v_mul_f32_e32 v53, s50, v53
	v_add_f32_e32 v58, 1.0, v58
	v_add_f32_e32 v61, 1.0, v61
	v_log_f32_e32 v58, v58
	v_log_f32_e32 v61, v61
	v_fmamk_f32 v58, v58, 0xbd317218, v52
	v_fmamk_f32 v59, v61, 0xbd317218, v53
	v_add_f32_e32 v53, v78, v54
	v_add_f32_e32 v52, v58, v60
	v_add_f32_e32 v60, v59, v52
	v_min_f32_e32 v52, 0, v53
	v_min_f32_e32 v54, 0, v55
	v_mul_f32_e64 v53, |v53|, s33
	v_mul_f32_e64 v55, |v55|, s33
	v_exp_f32_e32 v53, v53
	v_exp_f32_e32 v55, v55
	v_mul_f32_e32 v52, s50, v52
	v_mul_f32_e32 v54, s50, v54
	v_add_f32_e32 v53, 1.0, v53
	v_add_f32_e32 v55, 1.0, v55
	v_log_f32_e32 v53, v53
	v_log_f32_e32 v55, v55
	v_fmamk_f32 v64, v53, 0xbd317218, v52
	v_fmamk_f32 v65, v55, 0xbd317218, v54
	s_nop 0
	v_add_f32_e32 v52, v64, v60
	v_add_f32_e32 v52, v65, v52
	ds_bpermute_b32 v53, v91, v52
	s_waitcnt lgkmcnt(0)
	v_add_f32_e32 v52, v52, v53
	ds_bpermute_b32 v53, v116, v52
	s_and_saveexec_b64 s[0:1], s[40:41]
	s_cbranch_execz .LBB0_342
	s_waitcnt lgkmcnt(0)
	v_add_f32_e32 v52, v52, v53
	v_mul_f32_e32 v52, 0x3fb8aa3b, v52
	v_exp_f32_e32 v54, v52
	v_lshl_add_u64 v[52:53], v[32:33], 0, v[176:177]
	global_store_dword v[52:53], v54, off offset:16
; __device__ __forceinline__ f32x4 mfma16(bf16x8 a, bf16x8 b, f32x4 c) { return __builtin_amdgcn_mfma_f32_16x16x32_bf16(a, b, c, 0, 0, 0); }
; template <int MODE> __device__ void mixer_gla(const Params& p, int l, int n, LAS unsigned char* lds) {
;     ...
;             for (int ef = 0; ef < 4; ++ef) { tot[ef] = 0.f;
; #pragma unroll
;                 for (int ks = 0; ks < 2; ++ks) { f32x4 la2[2];
; #pragma unroll
;                     for (int t2 = 0; t2 < 2; ++t2) { const f32x4 z = mfma16(lrf[2 * ks + t2], gwf[ef], zero4);
; #pragma unroll
;                         for (int r = 0; r < 4; ++r) { const float zz = z[r] + bgv[ef]; const float la = (fminf(zz, 0.f) - __logf(1.0f + __expf(-fabsf(zz)))) * (1.0f / 16.0f); la2[t2][r] = la; tot[ef] += la; } }
;                     laop[ef][ks] = pack8(la2[0], la2[1]); __builtin_amdgcn_sched_barrier(0); } }
;     ...
;             for (int ef = 0; ef < 4; ++ef) { float tt = tot[ef]; tt += __shfl_xor(tt, 16); tt += __shfl_xor(tt, 32);
;                 if (vh == 0 && q == 0) dec[((size_t)(dir * NCH + n) * 4 + h) * 64 + SIGC(ef, c)] = __expf(tt); }
.LBB0_342:
	s_or_b64 exec, exec, s[0:1]
	v_add_f32_e32 v52, v77, v48
	s_waitcnt lgkmcnt(0)
	v_add_f32_e32 v54, v77, v49
	v_min_f32_e32 v48, 0, v52
	v_min_f32_e32 v49, 0, v54
	v_mul_f32_e64 v52, |v52|, s33
	v_mul_f32_e64 v54, |v54|, s33
	v_exp_f32_e32 v52, v52
	v_exp_f32_e32 v54, v54
	v_mul_f32_e32 v48, s50, v48
	v_mul_f32_e32 v49, s50, v49
	v_add_f32_e32 v52, 1.0, v52
	v_add_f32_e32 v54, 1.0, v54
	v_log_f32_e32 v52, v52
	v_log_f32_e32 v54, v54
	v_fmamk_f32 v48, v52, 0xbd317218, v48
	v_fmamk_f32 v49, v54, 0xbd317218, v49
	s_nop 0
	v_add_f32_e32 v52, 0, v48
	v_add_f32_e32 v54, v49, v52
	v_add_f32_e32 v52, v77, v50
	v_add_f32_e32 v55, v77, v51
	v_min_f32_e32 v50, 0, v52
	v_min_f32_e32 v51, 0, v55
	v_mul_f32_e64 v52, |v52|, s33
	v_mul_f32_e64 v55, |v55|, s33
	v_exp_f32_e32 v52, v52
	v_exp_f32_e32 v55, v55
	v_mul_f32_e32 v50, s50, v50
	v_mul_f32_e32 v51, s50, v51
	v_add_f32_e32 v52, 1.0, v52
	v_add_f32_e32 v55, 1.0, v55
	v_log_f32_e32 v52, v52
	v_log_f32_e32 v55, v55
	v_fmamk_f32 v50, v52, 0xbd317218, v50
	v_fmamk_f32 v51, v55, 0xbd317218, v51
	s_nop 0
	v_add_f32_e32 v52, v50, v54
	v_add_f32_e32 v54, v51, v52
	v_add_f32_e32 v52, v77, v40
	v_add_f32_e32 v55, v77, v41
	v_min_f32_e32 v40, 0, v52
	v_min_f32_e32 v41, 0, v55
	v_mul_f32_e64 v52, |v52|, s33
	v_mul_f32_e64 v55, |v55|, s33
	v_exp_f32_e32 v52, v52
	v_exp_f32_e32 v55, v55
	v_mul_f32_e32 v40, s50, v40
	v_mul_f32_e32 v41, s50, v41
	v_add_f32_e32 v52, 1.0, v52
	v_add_f32_e32 v55, 1.0, v55
	v_log_f32_e32 v52, v52
	v_log_f32_e32 v55, v55
	v_fmamk_f32 v40, v52, 0xbd317218, v40
	v_fmamk_f32 v41, v55, 0xbd317218, v41
	s_nop 0
	v_add_f32_e32 v52, v40, v54
	v_add_f32_e32 v54, v41, v52
	v_add_f32_e32 v52, v77, v42
	v_add_f32_e32 v55, v77, v43
	v_min_f32_e32 v42, 0, v52
	v_min_f32_e32 v43, 0, v55
	v_mul_f32_e64 v52, |v52|, s33
	v_mul_f32_e64 v55, |v55|, s33
	v_exp_f32_e32 v52, v52
	v_exp_f32_e32 v55, v55
	v_mul_f32_e32 v42, s50, v42
	v_mul_f32_e32 v43, s50, v43
	v_add_f32_e32 v52, 1.0, v52
	v_add_f32_e32 v55, 1.0, v55
	v_log_f32_e32 v52, v52
	v_log_f32_e32 v55, v55
	v_fmamk_f32 v42, v52, 0xbd317218, v42
	v_fmamk_f32 v43, v55, 0xbd317218, v43
	s_nop 0
	v_add_f32_e32 v52, v42, v54
	v_add_f32_e32 v54, v43, v52
	v_add_f32_e32 v52, v77, v28
	v_add_f32_e32 v55, v77, v29
	v_min_f32_e32 v28, 0, v52
	v_min_f32_e32 v29, 0, v55
	v_mul_f32_e64 v52, |v52|, s33
	v_mul_f32_e64 v55, |v55|, s33
	v_exp_f32_e32 v52, v52
	v_exp_f32_e32 v55, v55
	v_mul_f32_e32 v28, s50, v28
	v_mul_f32_e32 v29, s50, v29
	v_add_f32_e32 v52, 1.0, v52
	v_add_f32_e32 v55, 1.0, v55
	v_log_f32_e32 v52, v52
	v_log_f32_e32 v55, v55
	v_fmamk_f32 v28, v52, 0xbd317218, v28
	v_fmamk_f32 v29, v55, 0xbd317218, v29
	s_nop 0
	v_add_f32_e32 v52, v28, v54
	v_add_f32_e32 v54, v29, v52
	v_add_f32_e32 v52, v77, v30
	v_add_f32_e32 v55, v77, v31
	v_min_f32_e32 v30, 0, v52
	v_min_f32_e32 v31, 0, v55
	v_mul_f32_e64 v52, |v52|, s33
	v_mul_f32_e64 v55, |v55|, s33
	v_exp_f32_e32 v52, v52
	v_exp_f32_e32 v55, v55
	v_mul_f32_e32 v30, s50, v30
	v_mul_f32_e32 v31, s50, v31
	v_add_f32_e32 v52, 1.0, v52
	v_add_f32_e32 v55, 1.0, v55
	v_log_f32_e32 v52, v52
	v_log_f32_e32 v55, v55
	v_fmamk_f32 v30, v52, 0xbd317218, v30
	v_fmamk_f32 v31, v55, 0xbd317218, v31
	s_nop 0
	v_add_f32_e32 v52, v30, v54
	v_add_f32_e32 v54, v31, v52
	v_add_f32_e32 v52, v77, v24
	v_add_f32_e32 v55, v77, v25
	v_min_f32_e32 v24, 0, v52
	v_min_f32_e32 v25, 0, v55
	v_mul_f32_e64 v52, |v52|, s33
	v_mul_f32_e64 v55, |v55|, s33
	v_exp_f32_e32 v52, v52
	v_exp_f32_e32 v55, v55
	v_mul_f32_e32 v24, s50, v24
	v_mul_f32_e32 v25, s50, v25
	v_add_f32_e32 v52, 1.0, v52
	v_add_f32_e32 v55, 1.0, v55
	v_log_f32_e32 v52, v52
	v_log_f32_e32 v55, v55
	v_fmamk_f32 v24, v52, 0xbd317218, v24
	v_fmamk_f32 v25, v55, 0xbd317218, v25
	s_nop 0
	v_add_f32_e32 v52, v24, v54
	v_add_f32_e32 v54, v25, v52
	v_add_f32_e32 v52, v77, v26
	v_add_f32_e32 v55, v77, v27
	v_min_f32_e32 v26, 0, v52
	v_min_f32_e32 v27, 0, v55
	v_mul_f32_e64 v52, |v52|, s33
	v_mul_f32_e64 v55, |v55|, s33
	v_exp_f32_e32 v52, v52
	v_exp_f32_e32 v55, v55
	v_mul_f32_e32 v26, s50, v26
	v_mul_f32_e32 v27, s50, v27
	v_add_f32_e32 v52, 1.0, v52
	v_add_f32_e32 v55, 1.0, v55
	v_log_f32_e32 v52, v52
	v_log_f32_e32 v55, v55
	v_fmamk_f32 v26, v52, 0xbd317218, v26
	v_fmamk_f32 v27, v55, 0xbd317218, v27
	s_nop 0
	v_add_f32_e32 v52, v26, v54
	v_add_f32_e32 v52, v27, v52
	ds_bpermute_b32 v53, v91, v52
	s_waitcnt lgkmcnt(0)
	v_add_f32_e32 v52, v52, v53
	ds_bpermute_b32 v53, v116, v52
	s_and_saveexec_b64 s[0:1], s[40:41]
	s_cbranch_execz .LBB0_344
	s_waitcnt lgkmcnt(0)
	v_add_f32_e32 v52, v52, v53
	v_mul_f32_e32 v52, 0x3fb8aa3b, v52
	v_exp_f32_e32 v54, v52
	v_lshl_add_u64 v[52:53], v[32:33], 0, v[176:177]
	global_store_dword v[52:53], v54, off offset:128
; __device__ __forceinline__ f32x4 mfma16(bf16x8 a, bf16x8 b, f32x4 c) { return __builtin_amdgcn_mfma_f32_16x16x32_bf16(a, b, c, 0, 0, 0); }
; template <int MODE> __device__ void mixer_gla(const Params& p, int l, int n, LAS unsigned char* lds) {
;     ...
;             for (int ef = 0; ef < 4; ++ef) { tot[ef] = 0.f;
; #pragma unroll
;                 for (int ks = 0; ks < 2; ++ks) { f32x4 la2[2];
; #pragma unroll
;                     for (int t2 = 0; t2 < 2; ++t2) { const f32x4 z = mfma16(lrf[2 * ks + t2], gwf[ef], zero4);
; #pragma unroll
;                         for (int r = 0; r < 4; ++r) { const float zz = z[r] + bgv[ef]; const float la = (fminf(zz, 0.f) - __logf(1.0f + __expf(-fabsf(zz)))) * (1.0f / 16.0f); la2[t2][r] = la; tot[ef] += la; } }
;                     laop[ef][ks] = pack8(la2[0], la2[1]); __builtin_amdgcn_sched_barrier(0); } }
;     ...
;             for (int ef = 0; ef < 4; ++ef) { float tt = tot[ef]; tt += __shfl_xor(tt, 16); tt += __shfl_xor(tt, 32);
;                 if (vh == 0 && q == 0) dec[((size_t)(dir * NCH + n) * 4 + h) * 64 + SIGC(ef, c)] = __expf(tt); }
.LBB0_344:
	s_or_b64 exec, exec, s[0:1]
	s_waitcnt vmcnt(0)
	v_add_f32_e32 v52, v76, v20
	s_waitcnt lgkmcnt(0)
	v_add_f32_e32 v54, v76, v21
	v_min_f32_e32 v20, 0, v52
	v_min_f32_e32 v21, 0, v54
	v_mul_f32_e64 v52, |v52|, s33
	v_mul_f32_e64 v54, |v54|, s33
	v_exp_f32_e32 v52, v52
	v_exp_f32_e32 v54, v54
	v_mul_f32_e32 v20, s50, v20
	v_mul_f32_e32 v21, s50, v21
	v_add_f32_e32 v52, 1.0, v52
	v_add_f32_e32 v54, 1.0, v54
	v_log_f32_e32 v52, v52
	v_log_f32_e32 v54, v54
	v_fmamk_f32 v20, v52, 0xbd317218, v20
	v_fmamk_f32 v21, v54, 0xbd317218, v21
	s_nop 0
	v_add_f32_e32 v52, 0, v20
	v_add_f32_e32 v54, v21, v52
	v_add_f32_e32 v52, v76, v22
	v_add_f32_e32 v55, v76, v23
	v_min_f32_e32 v22, 0, v52
	v_min_f32_e32 v23, 0, v55
	v_mul_f32_e64 v52, |v52|, s33
	v_mul_f32_e64 v55, |v55|, s33
	v_exp_f32_e32 v52, v52
	v_exp_f32_e32 v55, v55
	v_mul_f32_e32 v22, s50, v22
	v_mul_f32_e32 v23, s50, v23
	v_add_f32_e32 v52, 1.0, v52
	v_add_f32_e32 v55, 1.0, v55
	v_log_f32_e32 v52, v52
	v_log_f32_e32 v55, v55
	v_fmamk_f32 v22, v52, 0xbd317218, v22
	v_fmamk_f32 v23, v55, 0xbd317218, v23
	s_nop 0
	v_add_f32_e32 v52, v22, v54
	v_add_f32_e32 v54, v23, v52
	v_add_f32_e32 v52, v76, v16
	v_add_f32_e32 v55, v76, v17
	v_min_f32_e32 v16, 0, v52
	v_min_f32_e32 v17, 0, v55
	v_mul_f32_e64 v52, |v52|, s33
	v_mul_f32_e64 v55, |v55|, s33
	v_exp_f32_e32 v52, v52
	v_exp_f32_e32 v55, v55
	v_mul_f32_e32 v16, s50, v16
	v_mul_f32_e32 v17, s50, v17
	v_add_f32_e32 v52, 1.0, v52
	v_add_f32_e32 v55, 1.0, v55
	v_log_f32_e32 v52, v52
	v_log_f32_e32 v55, v55
	v_fmamk_f32 v16, v52, 0xbd317218, v16
	v_fmamk_f32 v17, v55, 0xbd317218, v17
	s_nop 0
	v_add_f32_e32 v52, v16, v54
	v_add_f32_e32 v54, v17, v52
	v_add_f32_e32 v52, v76, v18
	v_add_f32_e32 v55, v76, v19
	v_min_f32_e32 v18, 0, v52
	v_min_f32_e32 v19, 0, v55
	v_mul_f32_e64 v52, |v52|, s33
	v_mul_f32_e64 v55, |v55|, s33
	v_exp_f32_e32 v52, v52
	v_exp_f32_e32 v55, v55
	v_mul_f32_e32 v18, s50, v18
	v_mul_f32_e32 v19, s50, v19
	v_add_f32_e32 v52, 1.0, v52
	v_add_f32_e32 v55, 1.0, v55
	v_log_f32_e32 v52, v52
	v_log_f32_e32 v55, v55
	v_fmamk_f32 v18, v52, 0xbd317218, v18
	v_fmamk_f32 v19, v55, 0xbd317218, v19
	s_nop 0
	v_add_f32_e32 v52, v18, v54
	v_add_f32_e32 v54, v19, v52
	v_add_f32_e32 v52, v76, v12
	v_add_f32_e32 v55, v76, v13
	v_min_f32_e32 v12, 0, v52
	v_min_f32_e32 v13, 0, v55
	v_mul_f32_e64 v52, |v52|, s33
	v_mul_f32_e64 v55, |v55|, s33
	v_exp_f32_e32 v52, v52
	v_exp_f32_e32 v55, v55
	v_mul_f32_e32 v12, s50, v12
	v_mul_f32_e32 v13, s50, v13
	v_add_f32_e32 v52, 1.0, v52
	v_add_f32_e32 v55, 1.0, v55
	v_log_f32_e32 v52, v52
	v_log_f32_e32 v55, v55
	v_fmamk_f32 v12, v52, 0xbd317218, v12
	v_fmamk_f32 v13, v55, 0xbd317218, v13
	s_nop 0
	v_add_f32_e32 v52, v12, v54
	v_add_f32_e32 v54, v13, v52
	v_add_f32_e32 v52, v76, v14
	v_add_f32_e32 v55, v76, v15
	v_min_f32_e32 v14, 0, v52
	v_min_f32_e32 v15, 0, v55
	v_mul_f32_e64 v52, |v52|, s33
	v_mul_f32_e64 v55, |v55|, s33
	v_exp_f32_e32 v52, v52
	v_exp_f32_e32 v55, v55
	v_mul_f32_e32 v14, s50, v14
	v_mul_f32_e32 v15, s50, v15
	v_add_f32_e32 v52, 1.0, v52
	v_add_f32_e32 v55, 1.0, v55
	v_log_f32_e32 v52, v52
	v_log_f32_e32 v55, v55
	v_fmamk_f32 v14, v52, 0xbd317218, v14
	v_fmamk_f32 v15, v55, 0xbd317218, v15
	s_nop 0
	v_add_f32_e32 v52, v14, v54
	v_add_f32_e32 v54, v15, v52
	v_add_f32_e32 v52, v76, v8
	v_add_f32_e32 v55, v76, v9
	v_min_f32_e32 v8, 0, v52
	v_min_f32_e32 v9, 0, v55
	v_mul_f32_e64 v52, |v52|, s33
	v_mul_f32_e64 v55, |v55|, s33
	v_exp_f32_e32 v52, v52
	v_exp_f32_e32 v55, v55
	v_mul_f32_e32 v8, s50, v8
	v_mul_f32_e32 v9, s50, v9
	v_add_f32_e32 v52, 1.0, v52
	v_add_f32_e32 v55, 1.0, v55
	v_log_f32_e32 v52, v52
	v_log_f32_e32 v55, v55
	v_fmamk_f32 v8, v52, 0xbd317218, v8
	v_fmamk_f32 v9, v55, 0xbd317218, v9
	s_nop 0
	v_add_f32_e32 v52, v8, v54
	v_add_f32_e32 v54, v9, v52
	v_add_f32_e32 v52, v76, v10
	v_add_f32_e32 v55, v76, v11
	v_min_f32_e32 v10, 0, v52
	v_min_f32_e32 v11, 0, v55
	v_mul_f32_e64 v52, |v52|, s33
	v_mul_f32_e64 v55, |v55|, s33
	v_exp_f32_e32 v52, v52
	v_exp_f32_e32 v55, v55
	v_mul_f32_e32 v10, s50, v10
	v_mul_f32_e32 v11, s50, v11
	v_add_f32_e32 v52, 1.0, v52
	v_add_f32_e32 v55, 1.0, v55
	v_log_f32_e32 v52, v52
	v_log_f32_e32 v55, v55
	v_fmamk_f32 v10, v52, 0xbd317218, v10
	v_fmamk_f32 v11, v55, 0xbd317218, v11
	s_nop 0
	v_add_f32_e32 v52, v10, v54
	v_add_f32_e32 v52, v11, v52
	ds_bpermute_b32 v53, v91, v52
	s_waitcnt lgkmcnt(0)
	v_add_f32_e32 v52, v52, v53
	ds_bpermute_b32 v53, v116, v52
	s_and_saveexec_b64 s[0:1], s[40:41]
	s_cbranch_execz .LBB0_329
	s_waitcnt lgkmcnt(0)
	v_add_f32_e32 v52, v52, v53
	v_mul_f32_e32 v52, 0x3fb8aa3b, v52
	v_exp_f32_e32 v52, v52
	v_lshl_add_u64 v[32:33], v[32:33], 0, v[176:177]
	global_store_dword v[32:33], v52, off offset:144
	s_branch .LBB0_329

; __device__ __forceinline__ WDesc wdesc(const Params& p, int l, int u) {
;     ...
;     if (v < T_IN) { const int rt = v / 16, kt = v % 16; int nv = DIN - rt * 64; nv = nv > 64 ? 64 : (nv < 0 ? 0 : nv);
;         d.src = p.in[3] + (size_t)l * D * DIN; d.ldsrc = DIN; d.c0 = nv > 0 ? rt * 64 : 0; d.nvalid = nv; d.k0 = kt * 64; d.dst = (bf16_t*)(ws + WS_WIN); d.lddst = D; d.r0 = rt * 64; return d; }
;     v -= T_IN;
;     if (v < T_OUT) { const int rt = v / 16, kt = v % 16; d.src = p.in[15] + (size_t)l * D * D; d.ldsrc = D; d.c0 = rt * 64; d.nvalid = 64; d.k0 = kt * 64; d.dst = (bf16_t*)(ws + WS_WOUT); d.lddst = D; d.r0 = rt * 64; return d; }
;     v -= T_OUT;
;     if (v < T_GU) { const int rt = v / 16, kt = v % 16; const int r0 = rt * 64, j = r0 / 256, within = r0 % 256;
;         d.src = (within < 128 ? p.in[18] : p.in[19]) + (size_t)l * D * DFF; d.ldsrc = DFF; d.c0 = j * 128 + (within & 127); d.nvalid = 64; d.k0 = kt * 64; d.dst = (bf16_t*)(ws + WS_WGU); d.lddst = D; d.r0 = r0; return d; }
;     v -= T_GU;
;     if (v < T_D) { const int rt = v / 44, kt = v % 44; d.src = p.in[20] + (size_t)l * DFF * D; d.ldsrc = D; d.c0 = rt * 64; d.nvalid = 64; d.k0 = kt * 64; d.dst = (bf16_t*)(ws + WS_WD); d.lddst = DFF; d.r0 = rt * 64; return d; }
;     v -= T_D;
;     { const int dir = v / 16, gate = (v / 8) % 2, h = v % 8; d.src = (gate ? p.in[8] : p.in[6]) + ((size_t)(l * 2 + dir) * 8 + h) * 4096; d.ldsrc = 64; d.c0 = 0; d.nvalid = 64; d.k0 = 0;
;       d.dst = (bf16_t*)(ws + WS_LRUW) + ((size_t)(dir * 2 + gate) * 8 + h) * 4096; d.lddst = 64; d.r0 = 0; return d; }
; }
; __device__ void phase_weights(const Params& p, int l, LAS unsigned char* lds) {
;     LAS float* T = (LAS float*)lds;
;     unsigned char* ws = p.ws;
;     constexpr int TOT = 44 * 16 + 16 * 16 + 88 * 16 + 16 * 44 + 32;
;     const int tid = otid(), G = gridDim.x;
;     for (int u0 = obid(); u0 < TOT; u0 += 4 * G) {
;         f32x4 v[4][2];
;         { const int k = tid >> 3, cg8 = (tid & 7) * 8;
; #pragma unroll
; template <int DIR> __device__ __forceinline__ void lru_dir(const Params& p, int l, int n, int h, int lane, LAS bf16_t* XC, LAS float* STA, LAS float* STU) {
;     ...
;         for (int r = 0; r < 4; ++r) { const float e = __expf(-lam4[r]); const float l1p = e < 0.05f ? e * (1.0f - e * (0.5f - e * (0.33333334f - e * 0.25f))) : __logf(1.0f + e); sp4[nf][r] = -8.0f * l1p; }
.LBB0_377:
	v_readlane_b32 s4, v255, 8
	v_readlane_b32 s5, v255, 9
	s_nop 2
	s_load_dword s26, s[4:5], 0x0
	s_waitcnt lgkmcnt(0)
	v_readlane_b32 s21, v254, 59
	v_readlane_b32 s51, v255, 16
	v_readfirstlane_b32 s20, v245
	s_nop 1
	s_cmp_lg_u32 s51, 0
	s_cbranch_scc1 .Lwp0_done
	s_cmp_ge_u32 s21, 8
	s_cbranch_scc1 .Lsptab_skip
	v_readlane_b32 s4, v254, 47
	v_readlane_b32 s5, v254, 48
	v_readlane_b32 s6, v255, 0
	v_readlane_b32 s7, v255, 1
	s_lshl_b32 s0, s21, 11
	v_lshlrev_b32_e32 v1, 2, v245
	v_add_u32_e32 v1, s0, v1
	s_nop 2
	global_load_dword v2, v1, s[4:5]
	s_add_u32 s6, s6, 0x4000
	s_addc_u32 s7, s7, 0
	v_mov_b32_e32 v4, 0xbe800000
	v_mov_b32_e32 v8, 0x3d4ccccd
	s_waitcnt vmcnt(0)
	v_mul_f32_e32 v3, 0xbfb8aa3b, v2
	v_exp_f32_e32 v3, v3
	s_nop 0
	v_fmaak_f32 v5, v3, v4, 0x3eaaaaab
	v_add_f32_e32 v6, 1.0, v3
	v_fma_f32 v5, -v3, v5, 0.5
	v_log_f32_e32 v6, v6
	v_fma_f32 v5, -v3, v5, 1.0
	v_mul_f32_e32 v7, 0x3f317217, v6
	v_mul_f32_e32 v5, v3, v5
	v_fma_f32 v7, v6, s36, -v7
	v_cmp_gt_f32_e32 vcc, v8, v3
	v_fmac_f32_e32 v7, 0x3377d1cf, v6
	v_fmac_f32_e32 v7, 0x3f317217, v6
	s_nop 0
	v_cndmask_b32_e32 v5, v7, v5, vcc
	global_store_dword v1, v5, s[6:7]
.Lsptab_skip:
	v_and_b32_e32 v0, 63, v245
	v_readlane_b32 s4, v254, 33
	v_readlane_b32 s5, v254, 34
	v_readlane_b32 s6, v254, 57
	v_readlane_b32 s7, v254, 58
	v_readlane_b32 s8, v253, 4
	v_readlane_b32 s9, v253, 5
	v_readlane_b32 s10, v253, 6
	v_readlane_b32 s11, v253, 7
	v_readlane_b32 s12, v254, 60
	v_readlane_b32 s13, v254, 61
	v_readlane_b32 s14, v254, 39
	v_readlane_b32 s15, v254, 40
	v_readlane_b32 s16, v254, 43
	v_readlane_b32 s17, v254, 44
	v_readlane_b32 s18, v255, 0
	v_readlane_b32 s19, v255, 1
	s_lshr_b32 s20, s20, 6
	s_lshl_b32 s31, s20, 14
	s_mul_i32 s0, s51, 0xa20000
	s_add_u32 s4, s4, s0
	s_addc_u32 s5, s5, 0
	s_lshl_b32 s0, s51, 22
	s_add_u32 s6, s6, s0
	s_addc_u32 s7, s7, 0
	s_mul_i32 s0, s51, 0xb00000
	s_add_u32 s8, s8, s0
	s_addc_u32 s9, s9, 0
	s_add_u32 s10, s10, s0
	s_addc_u32 s11, s11, 0
	s_add_u32 s12, s12, s0
	s_addc_u32 s13, s13, 0
	s_lshl_b32 s0, s51, 18
	s_add_u32 s14, s14, s0
	s_addc_u32 s15, s15, 0
	s_add_u32 s16, s16, s0
	s_addc_u32 s17, s17, 0
	v_lshrrev_b32_e32 v1, 4, v0
	v_and_b32_e32 v22, 15, v0
	v_xor_b32_e32 v2, 0, v22
	v_lshlrev_b32_e32 v2, 4, v2
	v_xor_b32_e32 v3, 1, v22
	v_lshlrev_b32_e32 v3, 4, v3
	v_xor_b32_e32 v4, 2, v22
	v_lshlrev_b32_e32 v4, 4, v4
	v_xor_b32_e32 v5, 3, v22
	v_lshlrev_b32_e32 v5, 4, v5
	v_xor_b32_e32 v6, 4, v22
	v_lshlrev_b32_e32 v6, 4, v6
	v_xor_b32_e32 v7, 5, v22
	v_lshlrev_b32_e32 v7, 4, v7
	v_xor_b32_e32 v8, 6, v22
	v_lshlrev_b32_e32 v8, 4, v8
	v_xor_b32_e32 v9, 7, v22
	v_lshlrev_b32_e32 v9, 4, v9
	v_lshrrev_b32_e32 v10, 3, v0
	v_and_b32_e32 v11, 7, v0
	v_lshrrev_b32_e32 v22, 2, v10
	v_and_b32_e32 v23, 3, v10
	v_lshlrev_b32_e32 v23, 2, v23
	v_lshl_add_u32 v23, v11, 11, v23
	v_add_u32_e32 v23, s31, v23
	v_add_u32_e32 v12, 0, v22
	v_xor_b32_e32 v12, v12, v11
	v_lshl_add_u32 v12, v12, 4, v23
	v_add_u32_e32 v13, 2, v22
	v_xor_b32_e32 v13, v13, v11
	v_lshl_add_u32 v13, v13, 4, v23
	v_add_u32_e32 v14, 4, v22
	v_xor_b32_e32 v14, v14, v11
	v_lshl_add_u32 v14, v14, 4, v23
	v_add_u32_e32 v15, 6, v22
	v_xor_b32_e32 v15, v15, v11
	v_lshl_add_u32 v15, v15, 4, v23
	v_add_u32_e32 v16, 8, v22
	v_xor_b32_e32 v16, v16, v11
	v_lshl_add_u32 v16, v16, 4, v23
	v_add_u32_e32 v17, 10, v22
	v_xor_b32_e32 v17, v17, v11
	v_lshl_add_u32 v17, v17, 4, v23
	v_add_u32_e32 v18, 12, v22
	v_xor_b32_e32 v18, v18, v11
	v_lshl_add_u32 v18, v18, 4, v23
	v_add_u32_e32 v19, 14, v22
	v_xor_b32_e32 v19, v19, v11
	v_lshl_add_u32 v19, v19, 4, v23
	s_mul_i32 s27, s20, 256
	s_add_u32 s27, s27, s21
